# v67 + removed the two temp LDS-base v_add per iteration in the 6 GEMM K-loops (immediate offsets instead)
# speedup vs baseline: 1.0191x; 1.0019x over previous
.LBB0_173:
	ds_read_b128 v[144:147], v155
	ds_read_b128 v[148:151], v155 offset:1024
	ds_read_b128 v[158:161], v155 offset:2048
	ds_read_b128 v[162:165], v155 offset:3072
	ds_read_b128 v[166:169], v156
	ds_read_b128 v[170:173], v156 offset:1024
	ds_read_b128 v[174:177], v156 offset:2048
	ds_read_b128 v[178:181], v156 offset:3072
	s_add_u32 s68, s66, 0xfff80080
	s_addc_u32 s69, s67, -1
	s_cmp_eq_u32 s77, 28
	s_cselect_b32 s71, s55, s69
	s_cselect_b32 s70, s59, s68
	s_cselect_b32 s69, s57, s76
	s_cselect_b32 s68, s65, s73
	s_add_i32 m0, s25, 0xc000
	ds_read_b128 v[182:185], v157
	ds_read_b128 v[186:189], v157 offset:1024
	ds_read_b128 v[190:193], v157 offset:2048
	ds_read_b128 v[194:197], v157 offset:3072
	ds_read_b128 v[198:201], v157 offset:4096
	ds_read_b128 v[202:205], v157 offset:5120
	ds_read_b128 v[206:209], v157 offset:6144
	ds_read_b128 v[210:213], v157 offset:7168
	global_load_lds_dwordx4 v136, s[66:67]
	s_add_i32 m0, s25, 0xe000
	s_nop 0
	global_load_lds_dwordx4 v138, s[66:67]
	s_waitcnt vmcnt(8)
	s_waitcnt lgkmcnt(0)
	s_setprio 1
	s_barrier
	v_mfma_i32_16x16x64_i8 v[124:127], v[144:147], v[182:185], v[124:127]
	v_mfma_i32_16x16x64_i8 v[116:119], v[158:161], v[182:185], v[116:119]
	v_mfma_i32_16x16x64_i8 v[108:111], v[144:147], v[190:193], v[108:111]
	v_mfma_i32_16x16x64_i8 v[100:103], v[158:161], v[190:193], v[100:103]
	v_mfma_i32_16x16x64_i8 v[92:95], v[144:147], v[198:201], v[92:95]
	v_mfma_i32_16x16x64_i8 v[84:87], v[158:161], v[198:201], v[84:87]
	v_mfma_i32_16x16x64_i8 v[76:79], v[144:147], v[206:209], v[76:79]
	v_mfma_i32_16x16x64_i8 v[68:71], v[158:161], v[206:209], v[68:71]
	v_mfma_i32_16x16x64_i8 v[124:127], v[148:151], v[186:189], v[124:127]
	v_mfma_i32_16x16x64_i8 v[116:119], v[162:165], v[186:189], v[116:119]
	v_mfma_i32_16x16x64_i8 v[108:111], v[148:151], v[194:197], v[108:111]
	v_mfma_i32_16x16x64_i8 v[100:103], v[162:165], v[194:197], v[100:103]
	v_mfma_i32_16x16x64_i8 v[92:95], v[148:151], v[202:205], v[92:95]
	v_mfma_i32_16x16x64_i8 v[84:87], v[162:165], v[202:205], v[84:87]
	v_mfma_i32_16x16x64_i8 v[76:79], v[148:151], v[210:213], v[76:79]
	v_mfma_i32_16x16x64_i8 v[68:71], v[162:165], v[210:213], v[68:71]
	v_mfma_i32_16x16x64_i8 v[120:123], v[166:169], v[182:185], v[120:123]
	v_mfma_i32_16x16x64_i8 v[112:115], v[174:177], v[182:185], v[112:115]
	v_mfma_i32_16x16x64_i8 v[104:107], v[166:169], v[190:193], v[104:107]
	v_mfma_i32_16x16x64_i8 v[96:99], v[174:177], v[190:193], v[96:99]
	v_mfma_i32_16x16x64_i8 v[88:91], v[166:169], v[198:201], v[88:91]
	v_mfma_i32_16x16x64_i8 v[80:83], v[174:177], v[198:201], v[80:83]
	v_mfma_i32_16x16x64_i8 v[72:75], v[166:169], v[206:209], v[72:75]
	v_mfma_i32_16x16x64_i8 v[64:67], v[174:177], v[206:209], v[64:67]
	v_mfma_i32_16x16x64_i8 v[120:123], v[170:173], v[186:189], v[120:123]
	v_mfma_i32_16x16x64_i8 v[112:115], v[178:181], v[186:189], v[112:115]
	v_mfma_i32_16x16x64_i8 v[104:107], v[170:173], v[194:197], v[104:107]
	v_mfma_i32_16x16x64_i8 v[96:99], v[178:181], v[194:197], v[96:99]
	v_mfma_i32_16x16x64_i8 v[88:91], v[170:173], v[202:205], v[88:91]
	v_mfma_i32_16x16x64_i8 v[80:83], v[178:181], v[202:205], v[80:83]
	v_mfma_i32_16x16x64_i8 v[72:75], v[170:173], v[210:213], v[72:75]
	v_mfma_i32_16x16x64_i8 v[64:67], v[178:181], v[210:213], v[64:67]
	s_barrier
	s_setprio 0
	s_add_i32 s78, s35, s13
	s_mov_b32 m0, s78
	ds_read_b128 v[182:185], v157 offset:16384
	ds_read_b128 v[186:189], v157 offset:17408
	ds_read_b128 v[190:193], v157 offset:18432
	ds_read_b128 v[194:197], v157 offset:19456
	ds_read_b128 v[198:201], v157 offset:20480
	ds_read_b128 v[202:205], v157 offset:21504
	ds_read_b128 v[206:209], v157 offset:22528
	ds_read_b128 v[210:213], v157 offset:23552
	global_load_lds_dwordx4 v132, s[68:69]
	s_add_i32 m0, s78, 0x2000
	s_add_u32 s78, s68, 0x80000
	s_mov_b64 s[98:99], s[68:69]
	s_addc_u32 s79, s69, 0
	s_add_i32 s81, s52, s13
	global_load_lds_dwordx4 v128, s[98:99]
	s_mov_b32 m0, s81
	s_mov_b64 s[100:101], s[70:71]
	global_load_lds_dwordx4 v132, s[78:79]
	s_add_i32 m0, s81, 0x2000
	s_nop 0
	global_load_lds_dwordx4 v128, s[78:79]
	s_mov_b64 s[100:101], s[70:71]
	s_mov_b32 m0, s25
	s_nop 0
	global_load_lds_dwordx4 v134, s[100:101]
	s_mov_b32 m0, s26
	s_nop 0
	global_load_lds_dwordx4 v130, s[100:101]
	s_waitcnt vmcnt(8)
	s_waitcnt lgkmcnt(0)
	s_setprio 1
	s_barrier
	v_mfma_i32_16x16x64_i8 v[60:63], v[144:147], v[182:185], v[60:63]
	v_mfma_i32_16x16x64_i8 v[52:55], v[158:161], v[182:185], v[52:55]
	v_mfma_i32_16x16x64_i8 v[44:47], v[144:147], v[190:193], v[44:47]
	v_mfma_i32_16x16x64_i8 v[36:39], v[158:161], v[190:193], v[36:39]
	v_mfma_i32_16x16x64_i8 v[28:31], v[144:147], v[198:201], v[28:31]
	v_mfma_i32_16x16x64_i8 v[20:23], v[158:161], v[198:201], v[20:23]
	v_mfma_i32_16x16x64_i8 v[12:15], v[144:147], v[206:209], v[12:15]
	v_mfma_i32_16x16x64_i8 v[4:7], v[158:161], v[206:209], v[4:7]
	v_mfma_i32_16x16x64_i8 v[60:63], v[148:151], v[186:189], v[60:63]
	v_mfma_i32_16x16x64_i8 v[52:55], v[162:165], v[186:189], v[52:55]
	v_mfma_i32_16x16x64_i8 v[44:47], v[148:151], v[194:197], v[44:47]
	v_mfma_i32_16x16x64_i8 v[36:39], v[162:165], v[194:197], v[36:39]
	v_mfma_i32_16x16x64_i8 v[28:31], v[148:151], v[202:205], v[28:31]
	v_mfma_i32_16x16x64_i8 v[20:23], v[162:165], v[202:205], v[20:23]
	v_mfma_i32_16x16x64_i8 v[12:15], v[148:151], v[210:213], v[12:15]
	v_mfma_i32_16x16x64_i8 v[4:7], v[162:165], v[210:213], v[4:7]
	v_mfma_i32_16x16x64_i8 v[56:59], v[166:169], v[182:185], v[56:59]
	v_mfma_i32_16x16x64_i8 v[48:51], v[174:177], v[182:185], v[48:51]
	v_mfma_i32_16x16x64_i8 v[40:43], v[166:169], v[190:193], v[40:43]
	v_mfma_i32_16x16x64_i8 v[32:35], v[174:177], v[190:193], v[32:35]
	v_mfma_i32_16x16x64_i8 v[24:27], v[166:169], v[198:201], v[24:27]
	v_mfma_i32_16x16x64_i8 v[16:19], v[174:177], v[198:201], v[16:19]
	v_mfma_i32_16x16x64_i8 v[8:11], v[166:169], v[206:209], v[8:11]
	v_mfma_i32_16x16x64_i8 v[0:3], v[174:177], v[206:209], v[0:3]
	v_mfma_i32_16x16x64_i8 v[56:59], v[170:173], v[186:189], v[56:59]
	v_mfma_i32_16x16x64_i8 v[48:51], v[178:181], v[186:189], v[48:51]
	v_mfma_i32_16x16x64_i8 v[40:43], v[170:173], v[194:197], v[40:43]
	v_mfma_i32_16x16x64_i8 v[32:35], v[178:181], v[194:197], v[32:35]
	v_mfma_i32_16x16x64_i8 v[24:27], v[170:173], v[202:205], v[24:27]
	v_mfma_i32_16x16x64_i8 v[16:19], v[178:181], v[202:205], v[16:19]
	v_mfma_i32_16x16x64_i8 v[8:11], v[170:173], v[210:213], v[8:11]
	v_mfma_i32_16x16x64_i8 v[0:3], v[178:181], v[210:213], v[0:3]
	s_barrier
	s_setprio 0
	s_add_i32 s78, 0, 0x18000
	s_add_i32 s79, 0, 0x1c000
	ds_read_b128 v[144:147], v155 offset:32768
	ds_read_b128 v[148:151], v155 offset:33792
	ds_read_b128 v[158:161], v155 offset:34816
	ds_read_b128 v[162:165], v155 offset:35840
	ds_read_b128 v[166:169], v156 offset:32768
	ds_read_b128 v[170:173], v156 offset:33792
	ds_read_b128 v[174:177], v156 offset:34816
	ds_read_b128 v[178:181], v156 offset:35840
	s_add_u32 s70, s70, 0x80000
	s_addc_u32 s71, s71, 0
	s_mov_b32 m0, s27
	ds_read_b128 v[182:185], v157 offset:32768
	ds_read_b128 v[186:189], v157 offset:33792
	ds_read_b128 v[190:193], v157 offset:34816
	ds_read_b128 v[194:197], v157 offset:35840
	ds_read_b128 v[198:201], v157 offset:36864
	ds_read_b128 v[202:205], v157 offset:37888
	ds_read_b128 v[206:209], v157 offset:38912
	ds_read_b128 v[210:213], v157 offset:39936
	global_load_lds_dwordx4 v134, s[70:71]
	s_mov_b32 m0, s28
	s_nop 0
	global_load_lds_dwordx4 v130, s[70:71]
	s_waitcnt vmcnt(8)
	s_waitcnt lgkmcnt(0)
	s_setprio 1
	s_barrier
	v_mfma_i32_16x16x64_i8 v[124:127], v[144:147], v[182:185], v[124:127]
	v_mfma_i32_16x16x64_i8 v[116:119], v[158:161], v[182:185], v[116:119]
	v_mfma_i32_16x16x64_i8 v[108:111], v[144:147], v[190:193], v[108:111]
	v_mfma_i32_16x16x64_i8 v[100:103], v[158:161], v[190:193], v[100:103]
	v_mfma_i32_16x16x64_i8 v[92:95], v[144:147], v[198:201], v[92:95]
	v_mfma_i32_16x16x64_i8 v[84:87], v[158:161], v[198:201], v[84:87]
	v_mfma_i32_16x16x64_i8 v[76:79], v[144:147], v[206:209], v[76:79]
	v_mfma_i32_16x16x64_i8 v[68:71], v[158:161], v[206:209], v[68:71]
	v_mfma_i32_16x16x64_i8 v[124:127], v[148:151], v[186:189], v[124:127]
	v_mfma_i32_16x16x64_i8 v[116:119], v[162:165], v[186:189], v[116:119]
	v_mfma_i32_16x16x64_i8 v[108:111], v[148:151], v[194:197], v[108:111]
	v_mfma_i32_16x16x64_i8 v[100:103], v[162:165], v[194:197], v[100:103]
	v_mfma_i32_16x16x64_i8 v[92:95], v[148:151], v[202:205], v[92:95]
	v_mfma_i32_16x16x64_i8 v[84:87], v[162:165], v[202:205], v[84:87]
	v_mfma_i32_16x16x64_i8 v[76:79], v[148:151], v[210:213], v[76:79]
	v_mfma_i32_16x16x64_i8 v[68:71], v[162:165], v[210:213], v[68:71]
	v_mfma_i32_16x16x64_i8 v[120:123], v[166:169], v[182:185], v[120:123]
	v_mfma_i32_16x16x64_i8 v[112:115], v[174:177], v[182:185], v[112:115]
	v_mfma_i32_16x16x64_i8 v[104:107], v[166:169], v[190:193], v[104:107]
	v_mfma_i32_16x16x64_i8 v[96:99], v[174:177], v[190:193], v[96:99]
	v_mfma_i32_16x16x64_i8 v[88:91], v[166:169], v[198:201], v[88:91]
	v_mfma_i32_16x16x64_i8 v[80:83], v[174:177], v[198:201], v[80:83]
	v_mfma_i32_16x16x64_i8 v[72:75], v[166:169], v[206:209], v[72:75]
	v_mfma_i32_16x16x64_i8 v[64:67], v[174:177], v[206:209], v[64:67]
	v_mfma_i32_16x16x64_i8 v[120:123], v[170:173], v[186:189], v[120:123]
	v_mfma_i32_16x16x64_i8 v[112:115], v[178:181], v[186:189], v[112:115]
	v_mfma_i32_16x16x64_i8 v[104:107], v[170:173], v[194:197], v[104:107]
	v_mfma_i32_16x16x64_i8 v[96:99], v[178:181], v[194:197], v[96:99]
	v_mfma_i32_16x16x64_i8 v[88:91], v[170:173], v[202:205], v[88:91]
	v_mfma_i32_16x16x64_i8 v[80:83], v[178:181], v[202:205], v[80:83]
	v_mfma_i32_16x16x64_i8 v[72:75], v[170:173], v[210:213], v[72:75]
	v_mfma_i32_16x16x64_i8 v[64:67], v[178:181], v[210:213], v[64:67]
	s_barrier
	s_setprio 0
	s_add_i32 s70, s78, s13
	s_add_i32 m0, s70, -128
	ds_read_b128 v[182:185], v157 offset:49152
	ds_read_b128 v[186:189], v157 offset:50176
	ds_read_b128 v[190:193], v157 offset:51200
	ds_read_b128 v[194:197], v157 offset:52224
	ds_read_b128 v[198:201], v157 offset:53248
	ds_read_b128 v[202:205], v157 offset:54272
	ds_read_b128 v[206:209], v157 offset:55296
	ds_read_b128 v[210:213], v157 offset:56320
	global_load_lds_dwordx4 v132, s[68:69] offset:128
	s_add_i32 m0, s70, 8064
	s_add_u32 s68, s68, 0x80080
	s_addc_u32 s69, s69, 0
	s_add_i32 s70, s79, s13
	global_load_lds_dwordx4 v128, s[98:99] offset:128
	s_mov_b32 m0, s70
	s_nop 0
	global_load_lds_dwordx4 v132, s[68:69]
	s_add_i32 m0, s70, 0x2000
	s_nop 0
	global_load_lds_dwordx4 v128, s[68:69]
	s_add_i32 m0, s31, -128
	s_nop 0
	global_load_lds_dwordx4 v134, s[100:101] offset:128
	s_add_i32 m0, s33, -128
	s_nop 0
	global_load_lds_dwordx4 v130, s[100:101] offset:128
	s_waitcnt vmcnt(8)
	s_waitcnt lgkmcnt(0)
	s_setprio 1
	s_barrier
	v_mfma_i32_16x16x64_i8 v[60:63], v[144:147], v[182:185], v[60:63]
	v_mfma_i32_16x16x64_i8 v[52:55], v[158:161], v[182:185], v[52:55]
	v_mfma_i32_16x16x64_i8 v[44:47], v[144:147], v[190:193], v[44:47]
	v_mfma_i32_16x16x64_i8 v[36:39], v[158:161], v[190:193], v[36:39]
	v_mfma_i32_16x16x64_i8 v[28:31], v[144:147], v[198:201], v[28:31]
	v_mfma_i32_16x16x64_i8 v[20:23], v[158:161], v[198:201], v[20:23]
	v_mfma_i32_16x16x64_i8 v[12:15], v[144:147], v[206:209], v[12:15]
	v_mfma_i32_16x16x64_i8 v[4:7], v[158:161], v[206:209], v[4:7]
	v_mfma_i32_16x16x64_i8 v[60:63], v[148:151], v[186:189], v[60:63]
	v_mfma_i32_16x16x64_i8 v[52:55], v[162:165], v[186:189], v[52:55]
	v_mfma_i32_16x16x64_i8 v[44:47], v[148:151], v[194:197], v[44:47]
	v_mfma_i32_16x16x64_i8 v[36:39], v[162:165], v[194:197], v[36:39]
	v_mfma_i32_16x16x64_i8 v[28:31], v[148:151], v[202:205], v[28:31]
	v_mfma_i32_16x16x64_i8 v[20:23], v[162:165], v[202:205], v[20:23]
	v_mfma_i32_16x16x64_i8 v[12:15], v[148:151], v[210:213], v[12:15]
	v_mfma_i32_16x16x64_i8 v[4:7], v[162:165], v[210:213], v[4:7]
	v_mfma_i32_16x16x64_i8 v[56:59], v[166:169], v[182:185], v[56:59]
	v_mfma_i32_16x16x64_i8 v[48:51], v[174:177], v[182:185], v[48:51]
	v_mfma_i32_16x16x64_i8 v[40:43], v[166:169], v[190:193], v[40:43]
	v_mfma_i32_16x16x64_i8 v[32:35], v[174:177], v[190:193], v[32:35]
	v_mfma_i32_16x16x64_i8 v[24:27], v[166:169], v[198:201], v[24:27]
	v_mfma_i32_16x16x64_i8 v[16:19], v[174:177], v[198:201], v[16:19]
	v_mfma_i32_16x16x64_i8 v[8:11], v[166:169], v[206:209], v[8:11]
	v_mfma_i32_16x16x64_i8 v[0:3], v[174:177], v[206:209], v[0:3]
	v_mfma_i32_16x16x64_i8 v[56:59], v[170:173], v[186:189], v[56:59]
	v_mfma_i32_16x16x64_i8 v[48:51], v[178:181], v[186:189], v[48:51]
	v_mfma_i32_16x16x64_i8 v[40:43], v[170:173], v[194:197], v[40:43]
	v_mfma_i32_16x16x64_i8 v[32:35], v[178:181], v[194:197], v[32:35]
	v_mfma_i32_16x16x64_i8 v[24:27], v[170:173], v[202:205], v[24:27]
	v_mfma_i32_16x16x64_i8 v[16:19], v[178:181], v[202:205], v[16:19]
	v_mfma_i32_16x16x64_i8 v[8:11], v[170:173], v[210:213], v[8:11]
	v_mfma_i32_16x16x64_i8 v[0:3], v[178:181], v[210:213], v[0:3]
	s_barrier
	s_setprio 0
	s_add_i32 s77, s77, 2
	s_add_u32 s66, s66, 0x100
	s_addc_u32 s67, s67, 0
	s_add_u32 s73, s73, 0x100
	s_addc_u32 s76, s76, 0
	s_cmp_gt_u32 s77, 29
	s_cbranch_scc0 .LBB0_173
	s_and_b64 vcc, exec, s[20:21]
	s_cbranch_vccz .LBB0_176
	s_barrier

.LBB0_258:
	ds_read_b128 v[152:155], v149
	ds_read_b128 v[156:159], v149 offset:1024
	ds_read_b128 v[160:163], v149 offset:2048
	ds_read_b128 v[164:167], v149 offset:3072
	ds_read_b128 v[168:171], v150
	ds_read_b128 v[172:175], v150 offset:1024
	ds_read_b128 v[176:179], v150 offset:2048
	ds_read_b128 v[180:183], v150 offset:3072
	s_add_u32 s36, s22, 0x100
	s_addc_u32 s37, s23, 0
	s_cmpk_eq_i32 s62, 0xa8
	s_cselect_b32 s57, s5, s37
	s_cselect_b32 s56, s4, s36
	s_cselect_b32 s41, s21, s61
	s_cselect_b32 s40, s20, s60
	s_add_i32 m0, s25, 0xc000
	ds_read_b128 v[184:187], v151
	ds_read_b128 v[188:191], v151 offset:1024
	ds_read_b128 v[192:195], v151 offset:2048
	ds_read_b128 v[196:199], v151 offset:3072
	ds_read_b128 v[200:203], v151 offset:4096
	ds_read_b128 v[204:207], v151 offset:5120
	ds_read_b128 v[208:211], v151 offset:6144
	ds_read_b128 v[212:215], v151 offset:7168
	global_load_lds_dwordx4 v136, s[22:23]
	s_add_i32 m0, s25, 0xe000
	s_nop 0
	global_load_lds_dwordx4 v138, s[22:23]
	s_waitcnt vmcnt(8)
	s_waitcnt lgkmcnt(0)
	s_setprio 1
	s_barrier
	v_mfma_f32_16x16x32_bf16 v[124:127], v[152:155], v[184:187], v[124:127]
	v_mfma_f32_16x16x32_bf16 v[120:123], v[160:163], v[184:187], v[120:123]
	v_mfma_f32_16x16x32_bf16 v[116:119], v[152:155], v[192:195], v[116:119]
	v_mfma_f32_16x16x32_bf16 v[108:111], v[160:163], v[192:195], v[108:111]
	v_mfma_f32_16x16x32_bf16 v[100:103], v[152:155], v[200:203], v[100:103]
	v_mfma_f32_16x16x32_bf16 v[92:95], v[160:163], v[200:203], v[92:95]
	v_mfma_f32_16x16x32_bf16 v[84:87], v[152:155], v[208:211], v[84:87]
	v_mfma_f32_16x16x32_bf16 v[76:79], v[160:163], v[208:211], v[76:79]
	v_mfma_f32_16x16x32_bf16 v[124:127], v[156:159], v[188:191], v[124:127]
	v_mfma_f32_16x16x32_bf16 v[120:123], v[164:167], v[188:191], v[120:123]
	v_mfma_f32_16x16x32_bf16 v[116:119], v[156:159], v[196:199], v[116:119]
	v_mfma_f32_16x16x32_bf16 v[108:111], v[164:167], v[196:199], v[108:111]
	v_mfma_f32_16x16x32_bf16 v[100:103], v[156:159], v[204:207], v[100:103]
	v_mfma_f32_16x16x32_bf16 v[92:95], v[164:167], v[204:207], v[92:95]
	v_mfma_f32_16x16x32_bf16 v[84:87], v[156:159], v[212:215], v[84:87]
	v_mfma_f32_16x16x32_bf16 v[76:79], v[164:167], v[212:215], v[76:79]
	v_mfma_f32_16x16x32_bf16 v[112:115], v[168:171], v[184:187], v[112:115]
	v_mfma_f32_16x16x32_bf16 v[104:107], v[176:179], v[184:187], v[104:107]
	v_mfma_f32_16x16x32_bf16 v[96:99], v[168:171], v[192:195], v[96:99]
	v_mfma_f32_16x16x32_bf16 v[88:91], v[176:179], v[192:195], v[88:91]
	v_mfma_f32_16x16x32_bf16 v[80:83], v[168:171], v[200:203], v[80:83]
	v_mfma_f32_16x16x32_bf16 v[72:75], v[176:179], v[200:203], v[72:75]
	v_mfma_f32_16x16x32_bf16 v[68:71], v[168:171], v[208:211], v[68:71]
	v_mfma_f32_16x16x32_bf16 v[64:67], v[176:179], v[208:211], v[64:67]
	v_mfma_f32_16x16x32_bf16 v[112:115], v[172:175], v[188:191], v[112:115]
	v_mfma_f32_16x16x32_bf16 v[104:107], v[180:183], v[188:191], v[104:107]
	v_mfma_f32_16x16x32_bf16 v[96:99], v[172:175], v[196:199], v[96:99]
	v_mfma_f32_16x16x32_bf16 v[88:91], v[180:183], v[196:199], v[88:91]
	v_mfma_f32_16x16x32_bf16 v[80:83], v[172:175], v[204:207], v[80:83]
	v_mfma_f32_16x16x32_bf16 v[72:75], v[180:183], v[204:207], v[72:75]
	v_mfma_f32_16x16x32_bf16 v[68:71], v[172:175], v[212:215], v[68:71]
	v_mfma_f32_16x16x32_bf16 v[64:67], v[180:183], v[212:215], v[64:67]
	s_barrier
	s_setprio 0
	s_add_i32 s22, s35, s3
	s_mov_b32 m0, s22
	ds_read_b128 v[184:187], v151 offset:16384
	ds_read_b128 v[188:191], v151 offset:17408
	ds_read_b128 v[192:195], v151 offset:18432
	ds_read_b128 v[196:199], v151 offset:19456
	ds_read_b128 v[200:203], v151 offset:20480
	ds_read_b128 v[204:207], v151 offset:21504
	ds_read_b128 v[208:211], v151 offset:22528
	ds_read_b128 v[212:215], v151 offset:23552
	global_load_lds_dwordx4 v132, s[40:41]
	s_add_i32 m0, s22, 0x2000
	s_add_u32 s22, s40, 0x2b0000
	s_mov_b64 s[98:99], s[40:41]
	s_addc_u32 s23, s41, 0
	s_add_i32 s63, s52, s3
	global_load_lds_dwordx4 v128, s[98:99]
	s_mov_b32 m0, s63
	s_nop 0
	global_load_lds_dwordx4 v132, s[22:23]
	s_add_i32 m0, s63, 0x2000
	s_nop 0
	global_load_lds_dwordx4 v128, s[22:23]
	s_mov_b32 m0, s25
	s_nop 0
	global_load_lds_dwordx4 v134, s[56:57]
	s_mov_b32 m0, s26
	s_nop 0
	global_load_lds_dwordx4 v130, s[56:57]
	s_waitcnt vmcnt(8)
	s_waitcnt lgkmcnt(0)
	s_setprio 1
	s_barrier
	v_mfma_f32_16x16x32_bf16 v[60:63], v[152:155], v[184:187], v[60:63]
	v_mfma_f32_16x16x32_bf16 v[56:59], v[160:163], v[184:187], v[56:59]
	v_mfma_f32_16x16x32_bf16 v[52:55], v[152:155], v[192:195], v[52:55]
	v_mfma_f32_16x16x32_bf16 v[44:47], v[160:163], v[192:195], v[44:47]
	v_mfma_f32_16x16x32_bf16 v[36:39], v[152:155], v[200:203], v[36:39]
	v_mfma_f32_16x16x32_bf16 v[28:31], v[160:163], v[200:203], v[28:31]
	v_mfma_f32_16x16x32_bf16 v[20:23], v[152:155], v[208:211], v[20:23]
	v_mfma_f32_16x16x32_bf16 v[12:15], v[160:163], v[208:211], v[12:15]
	v_mfma_f32_16x16x32_bf16 v[60:63], v[156:159], v[188:191], v[60:63]
	v_mfma_f32_16x16x32_bf16 v[56:59], v[164:167], v[188:191], v[56:59]
	v_mfma_f32_16x16x32_bf16 v[52:55], v[156:159], v[196:199], v[52:55]
	v_mfma_f32_16x16x32_bf16 v[44:47], v[164:167], v[196:199], v[44:47]
	v_mfma_f32_16x16x32_bf16 v[36:39], v[156:159], v[204:207], v[36:39]
	v_mfma_f32_16x16x32_bf16 v[28:31], v[164:167], v[204:207], v[28:31]
	v_mfma_f32_16x16x32_bf16 v[20:23], v[156:159], v[212:215], v[20:23]
	v_mfma_f32_16x16x32_bf16 v[12:15], v[164:167], v[212:215], v[12:15]
	v_mfma_f32_16x16x32_bf16 v[48:51], v[168:171], v[184:187], v[48:51]
	v_mfma_f32_16x16x32_bf16 v[40:43], v[176:179], v[184:187], v[40:43]
	v_mfma_f32_16x16x32_bf16 v[32:35], v[168:171], v[192:195], v[32:35]
	v_mfma_f32_16x16x32_bf16 v[24:27], v[176:179], v[192:195], v[24:27]
	v_mfma_f32_16x16x32_bf16 v[16:19], v[168:171], v[200:203], v[16:19]
	v_mfma_f32_16x16x32_bf16 v[8:11], v[176:179], v[200:203], v[8:11]
	v_mfma_f32_16x16x32_bf16 v[4:7], v[168:171], v[208:211], v[4:7]
	v_mfma_f32_16x16x32_bf16 v[0:3], v[176:179], v[208:211], v[0:3]
	v_mfma_f32_16x16x32_bf16 v[48:51], v[172:175], v[188:191], v[48:51]
	v_mfma_f32_16x16x32_bf16 v[40:43], v[180:183], v[188:191], v[40:43]
	v_mfma_f32_16x16x32_bf16 v[32:35], v[172:175], v[196:199], v[32:35]
	v_mfma_f32_16x16x32_bf16 v[24:27], v[180:183], v[196:199], v[24:27]
	v_mfma_f32_16x16x32_bf16 v[16:19], v[172:175], v[204:207], v[16:19]
	v_mfma_f32_16x16x32_bf16 v[8:11], v[180:183], v[204:207], v[8:11]
	v_mfma_f32_16x16x32_bf16 v[4:7], v[172:175], v[212:215], v[4:7]
	v_mfma_f32_16x16x32_bf16 v[0:3], v[180:183], v[212:215], v[0:3]
	s_barrier
	s_setprio 0
	s_add_i32 s63, 0, 0x18000
	s_add_i32 s64, 0, 0x1c000
	ds_read_b128 v[152:155], v149 offset:32768
	ds_read_b128 v[156:159], v149 offset:33792
	ds_read_b128 v[160:163], v149 offset:34816
	ds_read_b128 v[164:167], v149 offset:35840
	ds_read_b128 v[168:171], v150 offset:32768
	ds_read_b128 v[172:175], v150 offset:33792
	ds_read_b128 v[176:179], v150 offset:34816
	ds_read_b128 v[180:183], v150 offset:35840
	s_add_u32 s22, s56, 0x2b0000
	s_addc_u32 s23, s57, 0
	s_mov_b32 m0, s27
	ds_read_b128 v[184:187], v151 offset:32768
	ds_read_b128 v[188:191], v151 offset:33792
	ds_read_b128 v[192:195], v151 offset:34816
	ds_read_b128 v[196:199], v151 offset:35840
	ds_read_b128 v[200:203], v151 offset:36864
	ds_read_b128 v[204:207], v151 offset:37888
	ds_read_b128 v[208:211], v151 offset:38912
	ds_read_b128 v[212:215], v151 offset:39936
	global_load_lds_dwordx4 v134, s[22:23]
	s_mov_b32 m0, s28
	s_nop 0
	global_load_lds_dwordx4 v130, s[22:23]
	s_waitcnt vmcnt(8)
	s_waitcnt lgkmcnt(0)
	s_setprio 1
	s_barrier
	v_mfma_f32_16x16x32_bf16 v[124:127], v[152:155], v[184:187], v[124:127]
	v_mfma_f32_16x16x32_bf16 v[120:123], v[160:163], v[184:187], v[120:123]
	v_mfma_f32_16x16x32_bf16 v[116:119], v[152:155], v[192:195], v[116:119]
	v_mfma_f32_16x16x32_bf16 v[108:111], v[160:163], v[192:195], v[108:111]
	v_mfma_f32_16x16x32_bf16 v[100:103], v[152:155], v[200:203], v[100:103]
	v_mfma_f32_16x16x32_bf16 v[92:95], v[160:163], v[200:203], v[92:95]
	v_mfma_f32_16x16x32_bf16 v[84:87], v[152:155], v[208:211], v[84:87]
	v_mfma_f32_16x16x32_bf16 v[76:79], v[160:163], v[208:211], v[76:79]
	v_mfma_f32_16x16x32_bf16 v[124:127], v[156:159], v[188:191], v[124:127]
	v_mfma_f32_16x16x32_bf16 v[120:123], v[164:167], v[188:191], v[120:123]
	v_mfma_f32_16x16x32_bf16 v[116:119], v[156:159], v[196:199], v[116:119]
	v_mfma_f32_16x16x32_bf16 v[108:111], v[164:167], v[196:199], v[108:111]
	v_mfma_f32_16x16x32_bf16 v[100:103], v[156:159], v[204:207], v[100:103]
	v_mfma_f32_16x16x32_bf16 v[92:95], v[164:167], v[204:207], v[92:95]
	v_mfma_f32_16x16x32_bf16 v[84:87], v[156:159], v[212:215], v[84:87]
	v_mfma_f32_16x16x32_bf16 v[76:79], v[164:167], v[212:215], v[76:79]
	v_mfma_f32_16x16x32_bf16 v[112:115], v[168:171], v[184:187], v[112:115]
	v_mfma_f32_16x16x32_bf16 v[104:107], v[176:179], v[184:187], v[104:107]
	v_mfma_f32_16x16x32_bf16 v[96:99], v[168:171], v[192:195], v[96:99]
	v_mfma_f32_16x16x32_bf16 v[88:91], v[176:179], v[192:195], v[88:91]
	v_mfma_f32_16x16x32_bf16 v[80:83], v[168:171], v[200:203], v[80:83]
	v_mfma_f32_16x16x32_bf16 v[72:75], v[176:179], v[200:203], v[72:75]
	v_mfma_f32_16x16x32_bf16 v[68:71], v[168:171], v[208:211], v[68:71]
	v_mfma_f32_16x16x32_bf16 v[64:67], v[176:179], v[208:211], v[64:67]
	v_mfma_f32_16x16x32_bf16 v[112:115], v[172:175], v[188:191], v[112:115]
	v_mfma_f32_16x16x32_bf16 v[104:107], v[180:183], v[188:191], v[104:107]
	v_mfma_f32_16x16x32_bf16 v[96:99], v[172:175], v[196:199], v[96:99]
	v_mfma_f32_16x16x32_bf16 v[88:91], v[180:183], v[196:199], v[88:91]
	v_mfma_f32_16x16x32_bf16 v[80:83], v[172:175], v[204:207], v[80:83]
	v_mfma_f32_16x16x32_bf16 v[72:75], v[180:183], v[204:207], v[72:75]
	v_mfma_f32_16x16x32_bf16 v[68:71], v[172:175], v[212:215], v[68:71]
	v_mfma_f32_16x16x32_bf16 v[64:67], v[180:183], v[212:215], v[64:67]
	s_barrier
	s_setprio 0
	s_add_i32 s22, s63, s3
	s_add_i32 m0, s22, -128
	ds_read_b128 v[184:187], v151 offset:49152
	ds_read_b128 v[188:191], v151 offset:50176
	ds_read_b128 v[192:195], v151 offset:51200
	ds_read_b128 v[196:199], v151 offset:52224
	ds_read_b128 v[200:203], v151 offset:53248
	ds_read_b128 v[204:207], v151 offset:54272
	ds_read_b128 v[208:211], v151 offset:55296
	ds_read_b128 v[212:215], v151 offset:56320
	global_load_lds_dwordx4 v132, s[40:41] offset:128
	s_add_i32 m0, s22, 8064
	s_add_u32 s22, s40, 0x2b0080
	s_addc_u32 s23, s41, 0
	s_add_i32 s40, s64, s3
	global_load_lds_dwordx4 v128, s[98:99] offset:128
	s_mov_b32 m0, s40
	s_nop 0
	global_load_lds_dwordx4 v132, s[22:23]
	s_add_i32 m0, s40, 0x2000
	s_nop 0
	global_load_lds_dwordx4 v128, s[22:23]
	s_add_i32 m0, s31, -128
	s_nop 0
	global_load_lds_dwordx4 v134, s[56:57] offset:128
	s_add_i32 m0, s33, -128
	s_nop 0
	global_load_lds_dwordx4 v130, s[56:57] offset:128
	s_waitcnt vmcnt(8)
	s_waitcnt lgkmcnt(0)
	s_setprio 1
	s_barrier
	v_mfma_f32_16x16x32_bf16 v[60:63], v[152:155], v[184:187], v[60:63]
	v_mfma_f32_16x16x32_bf16 v[56:59], v[160:163], v[184:187], v[56:59]
	v_mfma_f32_16x16x32_bf16 v[52:55], v[152:155], v[192:195], v[52:55]
	v_mfma_f32_16x16x32_bf16 v[44:47], v[160:163], v[192:195], v[44:47]
	v_mfma_f32_16x16x32_bf16 v[36:39], v[152:155], v[200:203], v[36:39]
	v_mfma_f32_16x16x32_bf16 v[28:31], v[160:163], v[200:203], v[28:31]
	v_mfma_f32_16x16x32_bf16 v[20:23], v[152:155], v[208:211], v[20:23]
	v_mfma_f32_16x16x32_bf16 v[12:15], v[160:163], v[208:211], v[12:15]
	v_mfma_f32_16x16x32_bf16 v[60:63], v[156:159], v[188:191], v[60:63]
	v_mfma_f32_16x16x32_bf16 v[56:59], v[164:167], v[188:191], v[56:59]
	v_mfma_f32_16x16x32_bf16 v[52:55], v[156:159], v[196:199], v[52:55]
	v_mfma_f32_16x16x32_bf16 v[44:47], v[164:167], v[196:199], v[44:47]
	v_mfma_f32_16x16x32_bf16 v[36:39], v[156:159], v[204:207], v[36:39]
	v_mfma_f32_16x16x32_bf16 v[28:31], v[164:167], v[204:207], v[28:31]
	v_mfma_f32_16x16x32_bf16 v[20:23], v[156:159], v[212:215], v[20:23]
	v_mfma_f32_16x16x32_bf16 v[12:15], v[164:167], v[212:215], v[12:15]
	v_mfma_f32_16x16x32_bf16 v[48:51], v[168:171], v[184:187], v[48:51]
	v_mfma_f32_16x16x32_bf16 v[40:43], v[176:179], v[184:187], v[40:43]
	v_mfma_f32_16x16x32_bf16 v[32:35], v[168:171], v[192:195], v[32:35]
	v_mfma_f32_16x16x32_bf16 v[24:27], v[176:179], v[192:195], v[24:27]
	v_mfma_f32_16x16x32_bf16 v[16:19], v[168:171], v[200:203], v[16:19]
	v_mfma_f32_16x16x32_bf16 v[8:11], v[176:179], v[200:203], v[8:11]
	v_mfma_f32_16x16x32_bf16 v[4:7], v[168:171], v[208:211], v[4:7]
	v_mfma_f32_16x16x32_bf16 v[0:3], v[176:179], v[208:211], v[0:3]
	v_mfma_f32_16x16x32_bf16 v[48:51], v[172:175], v[188:191], v[48:51]
	v_mfma_f32_16x16x32_bf16 v[40:43], v[180:183], v[188:191], v[40:43]
	v_mfma_f32_16x16x32_bf16 v[32:35], v[172:175], v[196:199], v[32:35]
	v_mfma_f32_16x16x32_bf16 v[24:27], v[180:183], v[196:199], v[24:27]
	v_mfma_f32_16x16x32_bf16 v[16:19], v[172:175], v[204:207], v[16:19]
	v_mfma_f32_16x16x32_bf16 v[8:11], v[180:183], v[204:207], v[8:11]
	v_mfma_f32_16x16x32_bf16 v[4:7], v[172:175], v[212:215], v[4:7]
	v_mfma_f32_16x16x32_bf16 v[0:3], v[180:183], v[212:215], v[0:3]
	s_barrier
	s_setprio 0
	s_add_i32 s62, s62, 2
	s_add_u32 s60, s60, 0x100
	s_addc_u32 s61, s61, 0
	s_cmpk_gt_u32 s62, 0xa9
	s_mov_b64 s[22:23], s[36:37]
	s_cbranch_scc0 .LBB0_258
	s_and_b64 vcc, exec, s[14:15]
	s_cbranch_vccz .LBB0_261
	s_barrier

.LBB0_394:
	ds_read_b128 v[156:159], v152
	ds_read_b128 v[160:163], v152 offset:1024
	ds_read_b128 v[164:167], v152 offset:2048
	ds_read_b128 v[168:171], v152 offset:3072
	ds_read_b128 v[172:175], v153
	ds_read_b128 v[176:179], v153 offset:1024
	ds_read_b128 v[180:183], v153 offset:2048
	ds_read_b128 v[184:187], v153 offset:3072
	s_add_u32 s40, s38, 0xfff00080
	s_addc_u32 s41, s39, -1
	s_cmp_eq_u32 s64, 60
	s_cselect_b32 s57, s21, s41
	s_cselect_b32 s56, s60, s40
	s_cselect_b32 s41, s15, s63
	s_cselect_b32 s40, s61, s62
	s_add_i32 m0, s29, 0xc000
	ds_read_b128 v[188:191], v154
	ds_read_b128 v[192:195], v154 offset:1024
	ds_read_b128 v[196:199], v154 offset:2048
	ds_read_b128 v[200:203], v154 offset:3072
	ds_read_b128 v[204:207], v154 offset:4096
	ds_read_b128 v[208:211], v154 offset:5120
	ds_read_b128 v[212:215], v154 offset:6144
	ds_read_b128 v[216:219], v154 offset:7168
	global_load_lds_dwordx4 v140, s[38:39]
	s_add_i32 m0, s29, 0xe000
	s_nop 0
	global_load_lds_dwordx4 v142, s[38:39]
	s_waitcnt vmcnt(8)
	s_waitcnt lgkmcnt(0)
	s_setprio 1
	s_barrier
	v_mfma_f32_16x16x32_bf16 v[124:127], v[156:159], v[188:191], v[124:127]
	v_mfma_f32_16x16x32_bf16 v[120:123], v[164:167], v[188:191], v[120:123]
	v_mfma_f32_16x16x32_bf16 v[112:115], v[156:159], v[196:199], v[112:115]
	v_mfma_f32_16x16x32_bf16 v[104:107], v[164:167], v[196:199], v[104:107]
	v_mfma_f32_16x16x32_bf16 v[96:99], v[156:159], v[204:207], v[96:99]
	v_mfma_f32_16x16x32_bf16 v[88:91], v[164:167], v[204:207], v[88:91]
	v_mfma_f32_16x16x32_bf16 v[80:83], v[156:159], v[212:215], v[80:83]
	v_mfma_f32_16x16x32_bf16 v[72:75], v[164:167], v[212:215], v[72:75]
	v_mfma_f32_16x16x32_bf16 v[124:127], v[160:163], v[192:195], v[124:127]
	v_mfma_f32_16x16x32_bf16 v[120:123], v[168:171], v[192:195], v[120:123]
	v_mfma_f32_16x16x32_bf16 v[112:115], v[160:163], v[200:203], v[112:115]
	v_mfma_f32_16x16x32_bf16 v[104:107], v[168:171], v[200:203], v[104:107]
	v_mfma_f32_16x16x32_bf16 v[96:99], v[160:163], v[208:211], v[96:99]
	v_mfma_f32_16x16x32_bf16 v[88:91], v[168:171], v[208:211], v[88:91]
	v_mfma_f32_16x16x32_bf16 v[80:83], v[160:163], v[216:219], v[80:83]
	v_mfma_f32_16x16x32_bf16 v[72:75], v[168:171], v[216:219], v[72:75]
	v_mfma_f32_16x16x32_bf16 v[116:119], v[172:175], v[188:191], v[116:119]
	v_mfma_f32_16x16x32_bf16 v[108:111], v[180:183], v[188:191], v[108:111]
	v_mfma_f32_16x16x32_bf16 v[100:103], v[172:175], v[196:199], v[100:103]
	v_mfma_f32_16x16x32_bf16 v[92:95], v[180:183], v[196:199], v[92:95]
	v_mfma_f32_16x16x32_bf16 v[84:87], v[172:175], v[204:207], v[84:87]
	v_mfma_f32_16x16x32_bf16 v[76:79], v[180:183], v[204:207], v[76:79]
	v_mfma_f32_16x16x32_bf16 v[68:71], v[172:175], v[212:215], v[68:71]
	v_mfma_f32_16x16x32_bf16 v[64:67], v[180:183], v[212:215], v[64:67]
	v_mfma_f32_16x16x32_bf16 v[116:119], v[176:179], v[192:195], v[116:119]
	v_mfma_f32_16x16x32_bf16 v[108:111], v[184:187], v[192:195], v[108:111]
	v_mfma_f32_16x16x32_bf16 v[100:103], v[176:179], v[200:203], v[100:103]
	v_mfma_f32_16x16x32_bf16 v[92:95], v[184:187], v[200:203], v[92:95]
	v_mfma_f32_16x16x32_bf16 v[84:87], v[176:179], v[208:211], v[84:87]
	v_mfma_f32_16x16x32_bf16 v[76:79], v[184:187], v[208:211], v[76:79]
	v_mfma_f32_16x16x32_bf16 v[68:71], v[176:179], v[216:219], v[68:71]
	v_mfma_f32_16x16x32_bf16 v[64:67], v[184:187], v[216:219], v[64:67]
	s_barrier
	s_setprio 0
	s_add_i32 s65, s58, s24
	s_mov_b32 m0, s65
	ds_read_b128 v[188:191], v154 offset:16384
	ds_read_b128 v[192:195], v154 offset:17408
	ds_read_b128 v[196:199], v154 offset:18432
	ds_read_b128 v[200:203], v154 offset:19456
	ds_read_b128 v[204:207], v154 offset:20480
	ds_read_b128 v[208:211], v154 offset:21504
	ds_read_b128 v[212:215], v154 offset:22528
	ds_read_b128 v[216:219], v154 offset:23552
	global_load_lds_dwordx4 v132, s[40:41]
	s_add_i32 m0, s65, 0x2000
	s_add_u32 s66, s40, 0x100000
	s_mov_b64 s[98:99], s[40:41]
	s_addc_u32 s67, s41, 0
	s_add_i32 s65, s59, s24
	global_load_lds_dwordx4 v128, s[98:99]
	s_mov_b32 m0, s65
	s_mov_b64 s[100:101], s[56:57]
	global_load_lds_dwordx4 v132, s[66:67]
	s_add_i32 m0, s65, 0x2000
	s_nop 0
	global_load_lds_dwordx4 v128, s[66:67]
	s_mov_b64 s[100:101], s[56:57]
	s_mov_b32 m0, s29
	s_nop 0
	global_load_lds_dwordx4 v134, s[100:101]
	s_mov_b32 m0, s30
	s_nop 0
	global_load_lds_dwordx4 v130, s[100:101]
	s_waitcnt vmcnt(8)
	s_waitcnt lgkmcnt(0)
	s_setprio 1
	s_barrier
	v_mfma_f32_16x16x32_bf16 v[60:63], v[156:159], v[188:191], v[60:63]
	v_mfma_f32_16x16x32_bf16 v[56:59], v[164:167], v[188:191], v[56:59]
	v_mfma_f32_16x16x32_bf16 v[52:55], v[156:159], v[196:199], v[52:55]
	v_mfma_f32_16x16x32_bf16 v[44:47], v[164:167], v[196:199], v[44:47]
	v_mfma_f32_16x16x32_bf16 v[36:39], v[156:159], v[204:207], v[36:39]
	v_mfma_f32_16x16x32_bf16 v[28:31], v[164:167], v[204:207], v[28:31]
	v_mfma_f32_16x16x32_bf16 v[20:23], v[156:159], v[212:215], v[20:23]
	v_mfma_f32_16x16x32_bf16 v[12:15], v[164:167], v[212:215], v[12:15]
	v_mfma_f32_16x16x32_bf16 v[60:63], v[160:163], v[192:195], v[60:63]
	v_mfma_f32_16x16x32_bf16 v[56:59], v[168:171], v[192:195], v[56:59]
	v_mfma_f32_16x16x32_bf16 v[52:55], v[160:163], v[200:203], v[52:55]
	v_mfma_f32_16x16x32_bf16 v[44:47], v[168:171], v[200:203], v[44:47]
	v_mfma_f32_16x16x32_bf16 v[36:39], v[160:163], v[208:211], v[36:39]
	v_mfma_f32_16x16x32_bf16 v[28:31], v[168:171], v[208:211], v[28:31]
	v_mfma_f32_16x16x32_bf16 v[20:23], v[160:163], v[216:219], v[20:23]
	v_mfma_f32_16x16x32_bf16 v[12:15], v[168:171], v[216:219], v[12:15]
	v_mfma_f32_16x16x32_bf16 v[48:51], v[172:175], v[188:191], v[48:51]
	v_mfma_f32_16x16x32_bf16 v[40:43], v[180:183], v[188:191], v[40:43]
	v_mfma_f32_16x16x32_bf16 v[32:35], v[172:175], v[196:199], v[32:35]
	v_mfma_f32_16x16x32_bf16 v[24:27], v[180:183], v[196:199], v[24:27]
	v_mfma_f32_16x16x32_bf16 v[16:19], v[172:175], v[204:207], v[16:19]
	v_mfma_f32_16x16x32_bf16 v[8:11], v[180:183], v[204:207], v[8:11]
	v_mfma_f32_16x16x32_bf16 v[4:7], v[172:175], v[212:215], v[4:7]
	v_mfma_f32_16x16x32_bf16 v[0:3], v[180:183], v[212:215], v[0:3]
	v_mfma_f32_16x16x32_bf16 v[48:51], v[176:179], v[192:195], v[48:51]
	v_mfma_f32_16x16x32_bf16 v[40:43], v[184:187], v[192:195], v[40:43]
	v_mfma_f32_16x16x32_bf16 v[32:35], v[176:179], v[200:203], v[32:35]
	v_mfma_f32_16x16x32_bf16 v[24:27], v[184:187], v[200:203], v[24:27]
	v_mfma_f32_16x16x32_bf16 v[16:19], v[176:179], v[208:211], v[16:19]
	v_mfma_f32_16x16x32_bf16 v[8:11], v[184:187], v[208:211], v[8:11]
	v_mfma_f32_16x16x32_bf16 v[4:7], v[176:179], v[216:219], v[4:7]
	v_mfma_f32_16x16x32_bf16 v[0:3], v[184:187], v[216:219], v[0:3]
	s_barrier
	s_setprio 0
	s_add_i32 s65, 0, 0x18000
	s_add_i32 s66, 0, 0x1c000
	ds_read_b128 v[156:159], v152 offset:32768
	ds_read_b128 v[160:163], v152 offset:33792
	ds_read_b128 v[164:167], v152 offset:34816
	ds_read_b128 v[168:171], v152 offset:35840
	ds_read_b128 v[172:175], v153 offset:32768
	ds_read_b128 v[176:179], v153 offset:33792
	ds_read_b128 v[180:183], v153 offset:34816
	ds_read_b128 v[184:187], v153 offset:35840
	s_add_u32 s56, s56, 0x100000
	s_addc_u32 s57, s57, 0
	s_mov_b32 m0, s31
	ds_read_b128 v[188:191], v154 offset:32768
	ds_read_b128 v[192:195], v154 offset:33792
	ds_read_b128 v[196:199], v154 offset:34816
	ds_read_b128 v[200:203], v154 offset:35840
	ds_read_b128 v[204:207], v154 offset:36864
	ds_read_b128 v[208:211], v154 offset:37888
	ds_read_b128 v[212:215], v154 offset:38912
	ds_read_b128 v[216:219], v154 offset:39936
	global_load_lds_dwordx4 v134, s[56:57]
	s_mov_b32 m0, s33
	s_nop 0
	global_load_lds_dwordx4 v130, s[56:57]
	s_waitcnt vmcnt(8)
	s_waitcnt lgkmcnt(0)
	s_setprio 1
	s_barrier
	v_mfma_f32_16x16x32_bf16 v[124:127], v[156:159], v[188:191], v[124:127]
	v_mfma_f32_16x16x32_bf16 v[120:123], v[164:167], v[188:191], v[120:123]
	v_mfma_f32_16x16x32_bf16 v[112:115], v[156:159], v[196:199], v[112:115]
	v_mfma_f32_16x16x32_bf16 v[104:107], v[164:167], v[196:199], v[104:107]
	v_mfma_f32_16x16x32_bf16 v[96:99], v[156:159], v[204:207], v[96:99]
	v_mfma_f32_16x16x32_bf16 v[88:91], v[164:167], v[204:207], v[88:91]
	v_mfma_f32_16x16x32_bf16 v[80:83], v[156:159], v[212:215], v[80:83]
	v_mfma_f32_16x16x32_bf16 v[72:75], v[164:167], v[212:215], v[72:75]
	v_mfma_f32_16x16x32_bf16 v[124:127], v[160:163], v[192:195], v[124:127]
	v_mfma_f32_16x16x32_bf16 v[120:123], v[168:171], v[192:195], v[120:123]
	v_mfma_f32_16x16x32_bf16 v[112:115], v[160:163], v[200:203], v[112:115]
	v_mfma_f32_16x16x32_bf16 v[104:107], v[168:171], v[200:203], v[104:107]
	v_mfma_f32_16x16x32_bf16 v[96:99], v[160:163], v[208:211], v[96:99]
	v_mfma_f32_16x16x32_bf16 v[88:91], v[168:171], v[208:211], v[88:91]
	v_mfma_f32_16x16x32_bf16 v[80:83], v[160:163], v[216:219], v[80:83]
	v_mfma_f32_16x16x32_bf16 v[72:75], v[168:171], v[216:219], v[72:75]
	v_mfma_f32_16x16x32_bf16 v[116:119], v[172:175], v[188:191], v[116:119]
	v_mfma_f32_16x16x32_bf16 v[108:111], v[180:183], v[188:191], v[108:111]
	v_mfma_f32_16x16x32_bf16 v[100:103], v[172:175], v[196:199], v[100:103]
	v_mfma_f32_16x16x32_bf16 v[92:95], v[180:183], v[196:199], v[92:95]
	v_mfma_f32_16x16x32_bf16 v[84:87], v[172:175], v[204:207], v[84:87]
	v_mfma_f32_16x16x32_bf16 v[76:79], v[180:183], v[204:207], v[76:79]
	v_mfma_f32_16x16x32_bf16 v[68:71], v[172:175], v[212:215], v[68:71]
	v_mfma_f32_16x16x32_bf16 v[64:67], v[180:183], v[212:215], v[64:67]
	v_mfma_f32_16x16x32_bf16 v[116:119], v[176:179], v[192:195], v[116:119]
	v_mfma_f32_16x16x32_bf16 v[108:111], v[184:187], v[192:195], v[108:111]
	v_mfma_f32_16x16x32_bf16 v[100:103], v[176:179], v[200:203], v[100:103]
	v_mfma_f32_16x16x32_bf16 v[92:95], v[184:187], v[200:203], v[92:95]
	v_mfma_f32_16x16x32_bf16 v[84:87], v[176:179], v[208:211], v[84:87]
	v_mfma_f32_16x16x32_bf16 v[76:79], v[184:187], v[208:211], v[76:79]
	v_mfma_f32_16x16x32_bf16 v[68:71], v[176:179], v[216:219], v[68:71]
	v_mfma_f32_16x16x32_bf16 v[64:67], v[184:187], v[216:219], v[64:67]
	s_barrier
	s_setprio 0
	s_add_i32 s56, s65, s24
	s_add_i32 m0, s56, -128
	ds_read_b128 v[188:191], v154 offset:49152
	ds_read_b128 v[192:195], v154 offset:50176
	ds_read_b128 v[196:199], v154 offset:51200
	ds_read_b128 v[200:203], v154 offset:52224
	ds_read_b128 v[204:207], v154 offset:53248
	ds_read_b128 v[208:211], v154 offset:54272
	ds_read_b128 v[212:215], v154 offset:55296
	ds_read_b128 v[216:219], v154 offset:56320
	global_load_lds_dwordx4 v132, s[40:41] offset:128
	s_add_i32 m0, s56, 8064
	s_add_u32 s40, s40, 0x100080
	s_addc_u32 s41, s41, 0
	s_add_i32 s56, s66, s24
	global_load_lds_dwordx4 v128, s[98:99] offset:128
	s_mov_b32 m0, s56
	s_nop 0
	global_load_lds_dwordx4 v132, s[40:41]
	s_add_i32 m0, s56, 0x2000
	s_nop 0
	global_load_lds_dwordx4 v128, s[40:41]
	s_add_i32 m0, s54, -128
	s_nop 0
	global_load_lds_dwordx4 v134, s[100:101] offset:128
	s_add_i32 m0, s55, -128
	s_nop 0
	global_load_lds_dwordx4 v130, s[100:101] offset:128
	s_waitcnt vmcnt(8)
	s_waitcnt lgkmcnt(0)
	s_setprio 1
	s_barrier
	v_mfma_f32_16x16x32_bf16 v[60:63], v[156:159], v[188:191], v[60:63]
	v_mfma_f32_16x16x32_bf16 v[56:59], v[164:167], v[188:191], v[56:59]
	v_mfma_f32_16x16x32_bf16 v[52:55], v[156:159], v[196:199], v[52:55]
	v_mfma_f32_16x16x32_bf16 v[44:47], v[164:167], v[196:199], v[44:47]
	v_mfma_f32_16x16x32_bf16 v[36:39], v[156:159], v[204:207], v[36:39]
	v_mfma_f32_16x16x32_bf16 v[28:31], v[164:167], v[204:207], v[28:31]
	v_mfma_f32_16x16x32_bf16 v[20:23], v[156:159], v[212:215], v[20:23]
	v_mfma_f32_16x16x32_bf16 v[12:15], v[164:167], v[212:215], v[12:15]
	v_mfma_f32_16x16x32_bf16 v[60:63], v[160:163], v[192:195], v[60:63]
	v_mfma_f32_16x16x32_bf16 v[56:59], v[168:171], v[192:195], v[56:59]
	v_mfma_f32_16x16x32_bf16 v[52:55], v[160:163], v[200:203], v[52:55]
	v_mfma_f32_16x16x32_bf16 v[44:47], v[168:171], v[200:203], v[44:47]
	v_mfma_f32_16x16x32_bf16 v[36:39], v[160:163], v[208:211], v[36:39]
	v_mfma_f32_16x16x32_bf16 v[28:31], v[168:171], v[208:211], v[28:31]
	v_mfma_f32_16x16x32_bf16 v[20:23], v[160:163], v[216:219], v[20:23]
	v_mfma_f32_16x16x32_bf16 v[12:15], v[168:171], v[216:219], v[12:15]
	v_mfma_f32_16x16x32_bf16 v[48:51], v[172:175], v[188:191], v[48:51]
	v_mfma_f32_16x16x32_bf16 v[40:43], v[180:183], v[188:191], v[40:43]
	v_mfma_f32_16x16x32_bf16 v[32:35], v[172:175], v[196:199], v[32:35]
	v_mfma_f32_16x16x32_bf16 v[24:27], v[180:183], v[196:199], v[24:27]
	v_mfma_f32_16x16x32_bf16 v[16:19], v[172:175], v[204:207], v[16:19]
	v_mfma_f32_16x16x32_bf16 v[8:11], v[180:183], v[204:207], v[8:11]
	v_mfma_f32_16x16x32_bf16 v[4:7], v[172:175], v[212:215], v[4:7]
	v_mfma_f32_16x16x32_bf16 v[0:3], v[180:183], v[212:215], v[0:3]
	v_mfma_f32_16x16x32_bf16 v[48:51], v[176:179], v[192:195], v[48:51]
	v_mfma_f32_16x16x32_bf16 v[40:43], v[184:187], v[192:195], v[40:43]
	v_mfma_f32_16x16x32_bf16 v[32:35], v[176:179], v[200:203], v[32:35]
	v_mfma_f32_16x16x32_bf16 v[24:27], v[184:187], v[200:203], v[24:27]
	v_mfma_f32_16x16x32_bf16 v[16:19], v[176:179], v[208:211], v[16:19]
	v_mfma_f32_16x16x32_bf16 v[8:11], v[184:187], v[208:211], v[8:11]
	v_mfma_f32_16x16x32_bf16 v[4:7], v[176:179], v[216:219], v[4:7]
	v_mfma_f32_16x16x32_bf16 v[0:3], v[184:187], v[216:219], v[0:3]
	s_barrier
	s_setprio 0
	s_add_i32 s64, s64, 2
	s_add_u32 s38, s38, 0x100
	s_addc_u32 s39, s39, 0
	s_add_u32 s62, s62, 0x100
	s_addc_u32 s63, s63, 0
	s_cmp_gt_u32 s64, 61
	s_cbranch_scc0 .LBB0_394
	s_and_b64 vcc, exec, s[12:13]
	s_cbranch_vccz .LBB0_397
	s_barrier

.LBB0_622:
	ds_read_b128 v[152:155], v149
	ds_read_b128 v[156:159], v149 offset:1024
	ds_read_b128 v[160:163], v149 offset:2048
	ds_read_b128 v[164:167], v149 offset:3072
	ds_read_b128 v[168:171], v150
	ds_read_b128 v[172:175], v150 offset:1024
	ds_read_b128 v[176:179], v150 offset:2048
	ds_read_b128 v[180:183], v150 offset:3072
	s_add_u32 s42, s40, 0xfff00080
	s_addc_u32 s43, s41, -1
	s_cmp_eq_u32 s61, 60
	s_cselect_b32 s45, s25, s43
	s_cselect_b32 s44, s57, s42
	s_cselect_b32 s43, s23, s60
	s_cselect_b32 s42, s58, s59
	s_add_i32 m0, s31, 0xc000
	ds_read_b128 v[184:187], v151
	ds_read_b128 v[188:191], v151 offset:1024
	ds_read_b128 v[192:195], v151 offset:2048
	ds_read_b128 v[196:199], v151 offset:3072
	ds_read_b128 v[200:203], v151 offset:4096
	ds_read_b128 v[204:207], v151 offset:5120
	ds_read_b128 v[208:211], v151 offset:6144
	ds_read_b128 v[212:215], v151 offset:7168
	global_load_lds_dwordx4 v136, s[40:41]
	s_add_i32 m0, s31, 0xe000
	s_nop 0
	global_load_lds_dwordx4 v138, s[40:41]
	s_waitcnt vmcnt(8)
	s_waitcnt lgkmcnt(0)
	s_setprio 1
	s_barrier
	v_mfma_f32_16x16x32_bf16 v[124:127], v[152:155], v[184:187], v[124:127]
	v_mfma_f32_16x16x32_bf16 v[120:123], v[160:163], v[184:187], v[120:123]
	v_mfma_f32_16x16x32_bf16 v[116:119], v[152:155], v[192:195], v[116:119]
	v_mfma_f32_16x16x32_bf16 v[108:111], v[160:163], v[192:195], v[108:111]
	v_mfma_f32_16x16x32_bf16 v[100:103], v[152:155], v[200:203], v[100:103]
	v_mfma_f32_16x16x32_bf16 v[92:95], v[160:163], v[200:203], v[92:95]
	v_mfma_f32_16x16x32_bf16 v[84:87], v[152:155], v[208:211], v[84:87]
	v_mfma_f32_16x16x32_bf16 v[76:79], v[160:163], v[208:211], v[76:79]
	v_mfma_f32_16x16x32_bf16 v[124:127], v[156:159], v[188:191], v[124:127]
	v_mfma_f32_16x16x32_bf16 v[120:123], v[164:167], v[188:191], v[120:123]
	v_mfma_f32_16x16x32_bf16 v[116:119], v[156:159], v[196:199], v[116:119]
	v_mfma_f32_16x16x32_bf16 v[108:111], v[164:167], v[196:199], v[108:111]
	v_mfma_f32_16x16x32_bf16 v[100:103], v[156:159], v[204:207], v[100:103]
	v_mfma_f32_16x16x32_bf16 v[92:95], v[164:167], v[204:207], v[92:95]
	v_mfma_f32_16x16x32_bf16 v[84:87], v[156:159], v[212:215], v[84:87]
	v_mfma_f32_16x16x32_bf16 v[76:79], v[164:167], v[212:215], v[76:79]
	v_mfma_f32_16x16x32_bf16 v[112:115], v[168:171], v[184:187], v[112:115]
	v_mfma_f32_16x16x32_bf16 v[104:107], v[176:179], v[184:187], v[104:107]
	v_mfma_f32_16x16x32_bf16 v[96:99], v[168:171], v[192:195], v[96:99]
	v_mfma_f32_16x16x32_bf16 v[88:91], v[176:179], v[192:195], v[88:91]
	v_mfma_f32_16x16x32_bf16 v[80:83], v[168:171], v[200:203], v[80:83]
	v_mfma_f32_16x16x32_bf16 v[72:75], v[176:179], v[200:203], v[72:75]
	v_mfma_f32_16x16x32_bf16 v[68:71], v[168:171], v[208:211], v[68:71]
	v_mfma_f32_16x16x32_bf16 v[64:67], v[176:179], v[208:211], v[64:67]
	v_mfma_f32_16x16x32_bf16 v[112:115], v[172:175], v[188:191], v[112:115]
	v_mfma_f32_16x16x32_bf16 v[104:107], v[180:183], v[188:191], v[104:107]
	v_mfma_f32_16x16x32_bf16 v[96:99], v[172:175], v[196:199], v[96:99]
	v_mfma_f32_16x16x32_bf16 v[88:91], v[180:183], v[196:199], v[88:91]
	v_mfma_f32_16x16x32_bf16 v[80:83], v[172:175], v[204:207], v[80:83]
	v_mfma_f32_16x16x32_bf16 v[72:75], v[180:183], v[204:207], v[72:75]
	v_mfma_f32_16x16x32_bf16 v[68:71], v[172:175], v[212:215], v[68:71]
	v_mfma_f32_16x16x32_bf16 v[64:67], v[180:183], v[212:215], v[64:67]
	s_barrier
	s_setprio 0
	s_add_i32 s62, s50, s29
	s_mov_b32 m0, s62
	ds_read_b128 v[184:187], v151 offset:16384
	ds_read_b128 v[188:191], v151 offset:17408
	ds_read_b128 v[192:195], v151 offset:18432
	ds_read_b128 v[196:199], v151 offset:19456
	ds_read_b128 v[200:203], v151 offset:20480
	ds_read_b128 v[204:207], v151 offset:21504
	ds_read_b128 v[208:211], v151 offset:22528
	ds_read_b128 v[212:215], v151 offset:23552
	global_load_lds_dwordx4 v132, s[42:43]
	s_add_i32 m0, s62, 0x2000
	s_add_u32 s62, s42, 0x100000
	s_mov_b64 s[98:99], s[42:43]
	s_addc_u32 s63, s43, 0
	s_add_i32 s64, s51, s29
	global_load_lds_dwordx4 v128, s[98:99]
	s_mov_b32 m0, s64
	s_mov_b64 s[100:101], s[44:45]
	global_load_lds_dwordx4 v132, s[62:63]
	s_add_i32 m0, s64, 0x2000
	s_nop 0
	global_load_lds_dwordx4 v128, s[62:63]
	s_mov_b64 s[100:101], s[44:45]
	s_mov_b32 m0, s31
	s_nop 0
	global_load_lds_dwordx4 v134, s[100:101]
	s_mov_b32 m0, s33
	s_nop 0
	global_load_lds_dwordx4 v130, s[100:101]
	s_waitcnt vmcnt(8)
	s_waitcnt lgkmcnt(0)
	s_setprio 1
	s_barrier
	v_mfma_f32_16x16x32_bf16 v[60:63], v[152:155], v[184:187], v[60:63]
	v_mfma_f32_16x16x32_bf16 v[56:59], v[160:163], v[184:187], v[56:59]
	v_mfma_f32_16x16x32_bf16 v[52:55], v[152:155], v[192:195], v[52:55]
	v_mfma_f32_16x16x32_bf16 v[44:47], v[160:163], v[192:195], v[44:47]
	v_mfma_f32_16x16x32_bf16 v[36:39], v[152:155], v[200:203], v[36:39]
	v_mfma_f32_16x16x32_bf16 v[28:31], v[160:163], v[200:203], v[28:31]
	v_mfma_f32_16x16x32_bf16 v[20:23], v[152:155], v[208:211], v[20:23]
	v_mfma_f32_16x16x32_bf16 v[12:15], v[160:163], v[208:211], v[12:15]
	v_mfma_f32_16x16x32_bf16 v[60:63], v[156:159], v[188:191], v[60:63]
	v_mfma_f32_16x16x32_bf16 v[56:59], v[164:167], v[188:191], v[56:59]
	v_mfma_f32_16x16x32_bf16 v[52:55], v[156:159], v[196:199], v[52:55]
	v_mfma_f32_16x16x32_bf16 v[44:47], v[164:167], v[196:199], v[44:47]
	v_mfma_f32_16x16x32_bf16 v[36:39], v[156:159], v[204:207], v[36:39]
	v_mfma_f32_16x16x32_bf16 v[28:31], v[164:167], v[204:207], v[28:31]
	v_mfma_f32_16x16x32_bf16 v[20:23], v[156:159], v[212:215], v[20:23]
	v_mfma_f32_16x16x32_bf16 v[12:15], v[164:167], v[212:215], v[12:15]
	v_mfma_f32_16x16x32_bf16 v[48:51], v[168:171], v[184:187], v[48:51]
	v_mfma_f32_16x16x32_bf16 v[40:43], v[176:179], v[184:187], v[40:43]
	v_mfma_f32_16x16x32_bf16 v[32:35], v[168:171], v[192:195], v[32:35]
	v_mfma_f32_16x16x32_bf16 v[24:27], v[176:179], v[192:195], v[24:27]
	v_mfma_f32_16x16x32_bf16 v[16:19], v[168:171], v[200:203], v[16:19]
	v_mfma_f32_16x16x32_bf16 v[8:11], v[176:179], v[200:203], v[8:11]
	v_mfma_f32_16x16x32_bf16 v[4:7], v[168:171], v[208:211], v[4:7]
	v_mfma_f32_16x16x32_bf16 v[0:3], v[176:179], v[208:211], v[0:3]
	v_mfma_f32_16x16x32_bf16 v[48:51], v[172:175], v[188:191], v[48:51]
	v_mfma_f32_16x16x32_bf16 v[40:43], v[180:183], v[188:191], v[40:43]
	v_mfma_f32_16x16x32_bf16 v[32:35], v[172:175], v[196:199], v[32:35]
	v_mfma_f32_16x16x32_bf16 v[24:27], v[180:183], v[196:199], v[24:27]
	v_mfma_f32_16x16x32_bf16 v[16:19], v[172:175], v[204:207], v[16:19]
	v_mfma_f32_16x16x32_bf16 v[8:11], v[180:183], v[204:207], v[8:11]
	v_mfma_f32_16x16x32_bf16 v[4:7], v[172:175], v[212:215], v[4:7]
	v_mfma_f32_16x16x32_bf16 v[0:3], v[180:183], v[212:215], v[0:3]
	s_barrier
	s_setprio 0
	s_add_i32 s62, 0, 0x18000
	s_add_i32 s63, 0, 0x1c000
	ds_read_b128 v[152:155], v149 offset:32768
	ds_read_b128 v[156:159], v149 offset:33792
	ds_read_b128 v[160:163], v149 offset:34816
	ds_read_b128 v[164:167], v149 offset:35840
	ds_read_b128 v[168:171], v150 offset:32768
	ds_read_b128 v[172:175], v150 offset:33792
	ds_read_b128 v[176:179], v150 offset:34816
	ds_read_b128 v[180:183], v150 offset:35840
	s_add_u32 s44, s44, 0x100000
	s_addc_u32 s45, s45, 0
	s_mov_b32 m0, s35
	ds_read_b128 v[184:187], v151 offset:32768
	ds_read_b128 v[188:191], v151 offset:33792
	ds_read_b128 v[192:195], v151 offset:34816
	ds_read_b128 v[196:199], v151 offset:35840
	ds_read_b128 v[200:203], v151 offset:36864
	ds_read_b128 v[204:207], v151 offset:37888
	ds_read_b128 v[208:211], v151 offset:38912
	ds_read_b128 v[212:215], v151 offset:39936
	global_load_lds_dwordx4 v134, s[44:45]
	s_mov_b32 m0, s39
	s_nop 0
	global_load_lds_dwordx4 v130, s[44:45]
	s_waitcnt vmcnt(8)
	s_waitcnt lgkmcnt(0)
	s_setprio 1
	s_barrier
	v_mfma_f32_16x16x32_bf16 v[124:127], v[152:155], v[184:187], v[124:127]
	v_mfma_f32_16x16x32_bf16 v[120:123], v[160:163], v[184:187], v[120:123]
	v_mfma_f32_16x16x32_bf16 v[116:119], v[152:155], v[192:195], v[116:119]
	v_mfma_f32_16x16x32_bf16 v[108:111], v[160:163], v[192:195], v[108:111]
	v_mfma_f32_16x16x32_bf16 v[100:103], v[152:155], v[200:203], v[100:103]
	v_mfma_f32_16x16x32_bf16 v[92:95], v[160:163], v[200:203], v[92:95]
	v_mfma_f32_16x16x32_bf16 v[84:87], v[152:155], v[208:211], v[84:87]
	v_mfma_f32_16x16x32_bf16 v[76:79], v[160:163], v[208:211], v[76:79]
	v_mfma_f32_16x16x32_bf16 v[124:127], v[156:159], v[188:191], v[124:127]
	v_mfma_f32_16x16x32_bf16 v[120:123], v[164:167], v[188:191], v[120:123]
	v_mfma_f32_16x16x32_bf16 v[116:119], v[156:159], v[196:199], v[116:119]
	v_mfma_f32_16x16x32_bf16 v[108:111], v[164:167], v[196:199], v[108:111]
	v_mfma_f32_16x16x32_bf16 v[100:103], v[156:159], v[204:207], v[100:103]
	v_mfma_f32_16x16x32_bf16 v[92:95], v[164:167], v[204:207], v[92:95]
	v_mfma_f32_16x16x32_bf16 v[84:87], v[156:159], v[212:215], v[84:87]
	v_mfma_f32_16x16x32_bf16 v[76:79], v[164:167], v[212:215], v[76:79]
	v_mfma_f32_16x16x32_bf16 v[112:115], v[168:171], v[184:187], v[112:115]
	v_mfma_f32_16x16x32_bf16 v[104:107], v[176:179], v[184:187], v[104:107]
	v_mfma_f32_16x16x32_bf16 v[96:99], v[168:171], v[192:195], v[96:99]
	v_mfma_f32_16x16x32_bf16 v[88:91], v[176:179], v[192:195], v[88:91]
	v_mfma_f32_16x16x32_bf16 v[80:83], v[168:171], v[200:203], v[80:83]
	v_mfma_f32_16x16x32_bf16 v[72:75], v[176:179], v[200:203], v[72:75]
	v_mfma_f32_16x16x32_bf16 v[68:71], v[168:171], v[208:211], v[68:71]
	v_mfma_f32_16x16x32_bf16 v[64:67], v[176:179], v[208:211], v[64:67]
	v_mfma_f32_16x16x32_bf16 v[112:115], v[172:175], v[188:191], v[112:115]
	v_mfma_f32_16x16x32_bf16 v[104:107], v[180:183], v[188:191], v[104:107]
	v_mfma_f32_16x16x32_bf16 v[96:99], v[172:175], v[196:199], v[96:99]
	v_mfma_f32_16x16x32_bf16 v[88:91], v[180:183], v[196:199], v[88:91]
	v_mfma_f32_16x16x32_bf16 v[80:83], v[172:175], v[204:207], v[80:83]
	v_mfma_f32_16x16x32_bf16 v[72:75], v[180:183], v[204:207], v[72:75]
	v_mfma_f32_16x16x32_bf16 v[68:71], v[172:175], v[212:215], v[68:71]
	v_mfma_f32_16x16x32_bf16 v[64:67], v[180:183], v[212:215], v[64:67]
	s_barrier
	s_setprio 0
	s_add_i32 s44, s62, s29
	s_add_i32 m0, s44, -128
	ds_read_b128 v[184:187], v151 offset:49152
	ds_read_b128 v[188:191], v151 offset:50176
	ds_read_b128 v[192:195], v151 offset:51200
	ds_read_b128 v[196:199], v151 offset:52224
	ds_read_b128 v[200:203], v151 offset:53248
	ds_read_b128 v[204:207], v151 offset:54272
	ds_read_b128 v[208:211], v151 offset:55296
	ds_read_b128 v[212:215], v151 offset:56320
	global_load_lds_dwordx4 v132, s[42:43] offset:128
	s_add_i32 m0, s44, 8064
	s_add_u32 s42, s42, 0x100080
	s_addc_u32 s43, s43, 0
	s_add_i32 s44, s63, s29
	global_load_lds_dwordx4 v128, s[98:99] offset:128
	s_mov_b32 m0, s44
	s_nop 0
	global_load_lds_dwordx4 v132, s[42:43]
	s_add_i32 m0, s44, 0x2000
	s_nop 0
	global_load_lds_dwordx4 v128, s[42:43]
	s_add_i32 m0, s48, -128
	s_nop 0
	global_load_lds_dwordx4 v134, s[100:101] offset:128
	s_add_i32 m0, s49, -128
	s_nop 0
	global_load_lds_dwordx4 v130, s[100:101] offset:128
	s_waitcnt vmcnt(8)
	s_waitcnt lgkmcnt(0)
	s_setprio 1
	s_barrier
	v_mfma_f32_16x16x32_bf16 v[60:63], v[152:155], v[184:187], v[60:63]
	v_mfma_f32_16x16x32_bf16 v[56:59], v[160:163], v[184:187], v[56:59]
	v_mfma_f32_16x16x32_bf16 v[52:55], v[152:155], v[192:195], v[52:55]
	v_mfma_f32_16x16x32_bf16 v[44:47], v[160:163], v[192:195], v[44:47]
	v_mfma_f32_16x16x32_bf16 v[36:39], v[152:155], v[200:203], v[36:39]
	v_mfma_f32_16x16x32_bf16 v[28:31], v[160:163], v[200:203], v[28:31]
	v_mfma_f32_16x16x32_bf16 v[20:23], v[152:155], v[208:211], v[20:23]
	v_mfma_f32_16x16x32_bf16 v[12:15], v[160:163], v[208:211], v[12:15]
	v_mfma_f32_16x16x32_bf16 v[60:63], v[156:159], v[188:191], v[60:63]
	v_mfma_f32_16x16x32_bf16 v[56:59], v[164:167], v[188:191], v[56:59]
	v_mfma_f32_16x16x32_bf16 v[52:55], v[156:159], v[196:199], v[52:55]
	v_mfma_f32_16x16x32_bf16 v[44:47], v[164:167], v[196:199], v[44:47]
	v_mfma_f32_16x16x32_bf16 v[36:39], v[156:159], v[204:207], v[36:39]
	v_mfma_f32_16x16x32_bf16 v[28:31], v[164:167], v[204:207], v[28:31]
	v_mfma_f32_16x16x32_bf16 v[20:23], v[156:159], v[212:215], v[20:23]
	v_mfma_f32_16x16x32_bf16 v[12:15], v[164:167], v[212:215], v[12:15]
	v_mfma_f32_16x16x32_bf16 v[48:51], v[168:171], v[184:187], v[48:51]
	v_mfma_f32_16x16x32_bf16 v[40:43], v[176:179], v[184:187], v[40:43]
	v_mfma_f32_16x16x32_bf16 v[32:35], v[168:171], v[192:195], v[32:35]
	v_mfma_f32_16x16x32_bf16 v[24:27], v[176:179], v[192:195], v[24:27]
	v_mfma_f32_16x16x32_bf16 v[16:19], v[168:171], v[200:203], v[16:19]
	v_mfma_f32_16x16x32_bf16 v[8:11], v[176:179], v[200:203], v[8:11]
	v_mfma_f32_16x16x32_bf16 v[4:7], v[168:171], v[208:211], v[4:7]
	v_mfma_f32_16x16x32_bf16 v[0:3], v[176:179], v[208:211], v[0:3]
	v_mfma_f32_16x16x32_bf16 v[48:51], v[172:175], v[188:191], v[48:51]
	v_mfma_f32_16x16x32_bf16 v[40:43], v[180:183], v[188:191], v[40:43]
	v_mfma_f32_16x16x32_bf16 v[32:35], v[172:175], v[196:199], v[32:35]
	v_mfma_f32_16x16x32_bf16 v[24:27], v[180:183], v[196:199], v[24:27]
	v_mfma_f32_16x16x32_bf16 v[16:19], v[172:175], v[204:207], v[16:19]
	v_mfma_f32_16x16x32_bf16 v[8:11], v[180:183], v[204:207], v[8:11]
	v_mfma_f32_16x16x32_bf16 v[4:7], v[172:175], v[212:215], v[4:7]
	v_mfma_f32_16x16x32_bf16 v[0:3], v[180:183], v[212:215], v[0:3]
	s_barrier
	s_setprio 0
	s_add_i32 s61, s61, 2
	s_add_u32 s40, s40, 0x100
	s_addc_u32 s41, s41, 0
	s_add_u32 s59, s59, 0x100
	s_addc_u32 s60, s60, 0
	s_cmp_gt_u32 s61, 61
	s_cbranch_scc0 .LBB0_622
	s_and_b64 vcc, exec, s[10:11]
	s_cbranch_vccz .LBB0_625
	s_barrier

.LBB0_773:
	ds_read_b128 v[144:147], v155
	ds_read_b128 v[148:151], v155 offset:1024
	ds_read_b128 v[158:161], v155 offset:2048
	ds_read_b128 v[162:165], v155 offset:3072
	ds_read_b128 v[166:169], v156
	ds_read_b128 v[170:173], v156 offset:1024
	ds_read_b128 v[174:177], v156 offset:2048
	ds_read_b128 v[178:181], v156 offset:3072
	s_add_u32 s36, s30, 0xfff80080
	s_addc_u32 s37, s31, -1
	s_cmp_eq_u32 s52, 28
	s_cselect_b32 s39, s23, s37
	s_cselect_b32 s38, s48, s36
	s_cselect_b32 s37, s21, s51
	s_cselect_b32 s36, s49, s50
	s_add_i32 m0, s17, 0xc000
	ds_read_b128 v[182:185], v157
	ds_read_b128 v[186:189], v157 offset:1024
	ds_read_b128 v[190:193], v157 offset:2048
	ds_read_b128 v[194:197], v157 offset:3072
	ds_read_b128 v[198:201], v157 offset:4096
	ds_read_b128 v[202:205], v157 offset:5120
	ds_read_b128 v[206:209], v157 offset:6144
	ds_read_b128 v[210:213], v157 offset:7168
	global_load_lds_dwordx4 v136, s[30:31]
	s_add_i32 m0, s17, 0xe000
	s_nop 0
	global_load_lds_dwordx4 v138, s[30:31]
	s_waitcnt vmcnt(8)
	s_waitcnt lgkmcnt(0)
	s_setprio 1
	s_barrier
	v_mfma_i32_16x16x64_i8 v[124:127], v[144:147], v[182:185], v[124:127]
	v_mfma_i32_16x16x64_i8 v[116:119], v[158:161], v[182:185], v[116:119]
	v_mfma_i32_16x16x64_i8 v[108:111], v[144:147], v[190:193], v[108:111]
	v_mfma_i32_16x16x64_i8 v[100:103], v[158:161], v[190:193], v[100:103]
	v_mfma_i32_16x16x64_i8 v[92:95], v[144:147], v[198:201], v[92:95]
	v_mfma_i32_16x16x64_i8 v[84:87], v[158:161], v[198:201], v[84:87]
	v_mfma_i32_16x16x64_i8 v[76:79], v[144:147], v[206:209], v[76:79]
	v_mfma_i32_16x16x64_i8 v[68:71], v[158:161], v[206:209], v[68:71]
	v_mfma_i32_16x16x64_i8 v[124:127], v[148:151], v[186:189], v[124:127]
	v_mfma_i32_16x16x64_i8 v[116:119], v[162:165], v[186:189], v[116:119]
	v_mfma_i32_16x16x64_i8 v[108:111], v[148:151], v[194:197], v[108:111]
	v_mfma_i32_16x16x64_i8 v[100:103], v[162:165], v[194:197], v[100:103]
	v_mfma_i32_16x16x64_i8 v[92:95], v[148:151], v[202:205], v[92:95]
	v_mfma_i32_16x16x64_i8 v[84:87], v[162:165], v[202:205], v[84:87]
	v_mfma_i32_16x16x64_i8 v[76:79], v[148:151], v[210:213], v[76:79]
	v_mfma_i32_16x16x64_i8 v[68:71], v[162:165], v[210:213], v[68:71]
	v_mfma_i32_16x16x64_i8 v[120:123], v[166:169], v[182:185], v[120:123]
	v_mfma_i32_16x16x64_i8 v[112:115], v[174:177], v[182:185], v[112:115]
	v_mfma_i32_16x16x64_i8 v[104:107], v[166:169], v[190:193], v[104:107]
	v_mfma_i32_16x16x64_i8 v[96:99], v[174:177], v[190:193], v[96:99]
	v_mfma_i32_16x16x64_i8 v[88:91], v[166:169], v[198:201], v[88:91]
	v_mfma_i32_16x16x64_i8 v[80:83], v[174:177], v[198:201], v[80:83]
	v_mfma_i32_16x16x64_i8 v[72:75], v[166:169], v[206:209], v[72:75]
	v_mfma_i32_16x16x64_i8 v[64:67], v[174:177], v[206:209], v[64:67]
	v_mfma_i32_16x16x64_i8 v[120:123], v[170:173], v[186:189], v[120:123]
	v_mfma_i32_16x16x64_i8 v[112:115], v[178:181], v[186:189], v[112:115]
	v_mfma_i32_16x16x64_i8 v[104:107], v[170:173], v[194:197], v[104:107]
	v_mfma_i32_16x16x64_i8 v[96:99], v[178:181], v[194:197], v[96:99]
	v_mfma_i32_16x16x64_i8 v[88:91], v[170:173], v[202:205], v[88:91]
	v_mfma_i32_16x16x64_i8 v[80:83], v[178:181], v[202:205], v[80:83]
	v_mfma_i32_16x16x64_i8 v[72:75], v[170:173], v[210:213], v[72:75]
	v_mfma_i32_16x16x64_i8 v[64:67], v[178:181], v[210:213], v[64:67]
	s_barrier
	s_setprio 0
	s_add_i32 s53, s44, s2
	s_mov_b32 m0, s53
	ds_read_b128 v[182:185], v157 offset:16384
	ds_read_b128 v[186:189], v157 offset:17408
	ds_read_b128 v[190:193], v157 offset:18432
	ds_read_b128 v[194:197], v157 offset:19456
	ds_read_b128 v[198:201], v157 offset:20480
	ds_read_b128 v[202:205], v157 offset:21504
	ds_read_b128 v[206:209], v157 offset:22528
	ds_read_b128 v[210:213], v157 offset:23552
	global_load_lds_dwordx4 v132, s[36:37]
	s_add_i32 m0, s53, 0x2000
	s_add_u32 s54, s36, 0x80000
	s_mov_b64 s[98:99], s[36:37]
	s_addc_u32 s55, s37, 0
	s_add_i32 s53, s45, s2
	global_load_lds_dwordx4 v128, s[98:99]
	s_mov_b32 m0, s53
	s_mov_b64 s[100:101], s[38:39]
	global_load_lds_dwordx4 v132, s[54:55]
	s_add_i32 m0, s53, 0x2000
	s_nop 0
	global_load_lds_dwordx4 v128, s[54:55]
	s_mov_b64 s[100:101], s[38:39]
	s_mov_b32 m0, s17
	s_nop 0
	global_load_lds_dwordx4 v134, s[100:101]
	s_mov_b32 m0, s29
	s_nop 0
	global_load_lds_dwordx4 v130, s[100:101]
	s_waitcnt vmcnt(8)
	s_waitcnt lgkmcnt(0)
	s_setprio 1
	s_barrier
	v_mfma_i32_16x16x64_i8 v[60:63], v[144:147], v[182:185], v[60:63]
	v_mfma_i32_16x16x64_i8 v[52:55], v[158:161], v[182:185], v[52:55]
	v_mfma_i32_16x16x64_i8 v[44:47], v[144:147], v[190:193], v[44:47]
	v_mfma_i32_16x16x64_i8 v[36:39], v[158:161], v[190:193], v[36:39]
	v_mfma_i32_16x16x64_i8 v[28:31], v[144:147], v[198:201], v[28:31]
	v_mfma_i32_16x16x64_i8 v[20:23], v[158:161], v[198:201], v[20:23]
	v_mfma_i32_16x16x64_i8 v[12:15], v[144:147], v[206:209], v[12:15]
	v_mfma_i32_16x16x64_i8 v[4:7], v[158:161], v[206:209], v[4:7]
	v_mfma_i32_16x16x64_i8 v[60:63], v[148:151], v[186:189], v[60:63]
	v_mfma_i32_16x16x64_i8 v[52:55], v[162:165], v[186:189], v[52:55]
	v_mfma_i32_16x16x64_i8 v[44:47], v[148:151], v[194:197], v[44:47]
	v_mfma_i32_16x16x64_i8 v[36:39], v[162:165], v[194:197], v[36:39]
	v_mfma_i32_16x16x64_i8 v[28:31], v[148:151], v[202:205], v[28:31]
	v_mfma_i32_16x16x64_i8 v[20:23], v[162:165], v[202:205], v[20:23]
	v_mfma_i32_16x16x64_i8 v[12:15], v[148:151], v[210:213], v[12:15]
	v_mfma_i32_16x16x64_i8 v[4:7], v[162:165], v[210:213], v[4:7]
	v_mfma_i32_16x16x64_i8 v[56:59], v[166:169], v[182:185], v[56:59]
	v_mfma_i32_16x16x64_i8 v[48:51], v[174:177], v[182:185], v[48:51]
	v_mfma_i32_16x16x64_i8 v[40:43], v[166:169], v[190:193], v[40:43]
	v_mfma_i32_16x16x64_i8 v[32:35], v[174:177], v[190:193], v[32:35]
	v_mfma_i32_16x16x64_i8 v[24:27], v[166:169], v[198:201], v[24:27]
	v_mfma_i32_16x16x64_i8 v[16:19], v[174:177], v[198:201], v[16:19]
	v_mfma_i32_16x16x64_i8 v[8:11], v[166:169], v[206:209], v[8:11]
	v_mfma_i32_16x16x64_i8 v[0:3], v[174:177], v[206:209], v[0:3]
	v_mfma_i32_16x16x64_i8 v[56:59], v[170:173], v[186:189], v[56:59]
	v_mfma_i32_16x16x64_i8 v[48:51], v[178:181], v[186:189], v[48:51]
	v_mfma_i32_16x16x64_i8 v[40:43], v[170:173], v[194:197], v[40:43]
	v_mfma_i32_16x16x64_i8 v[32:35], v[178:181], v[194:197], v[32:35]
	v_mfma_i32_16x16x64_i8 v[24:27], v[170:173], v[202:205], v[24:27]
	v_mfma_i32_16x16x64_i8 v[16:19], v[178:181], v[202:205], v[16:19]
	v_mfma_i32_16x16x64_i8 v[8:11], v[170:173], v[210:213], v[8:11]
	v_mfma_i32_16x16x64_i8 v[0:3], v[178:181], v[210:213], v[0:3]
	s_barrier
	s_setprio 0
	s_add_i32 s53, 0, 0x18000
	s_add_i32 s54, 0, 0x1c000
	ds_read_b128 v[144:147], v155 offset:32768
	ds_read_b128 v[148:151], v155 offset:33792
	ds_read_b128 v[158:161], v155 offset:34816
	ds_read_b128 v[162:165], v155 offset:35840
	ds_read_b128 v[166:169], v156 offset:32768
	ds_read_b128 v[170:173], v156 offset:33792
	ds_read_b128 v[174:177], v156 offset:34816
	ds_read_b128 v[178:181], v156 offset:35840
	s_add_u32 s38, s38, 0x80000
	s_addc_u32 s39, s39, 0
	s_mov_b32 m0, s33
	ds_read_b128 v[182:185], v157 offset:32768
	ds_read_b128 v[186:189], v157 offset:33792
	ds_read_b128 v[190:193], v157 offset:34816
	ds_read_b128 v[194:197], v157 offset:35840
	ds_read_b128 v[198:201], v157 offset:36864
	ds_read_b128 v[202:205], v157 offset:37888
	ds_read_b128 v[206:209], v157 offset:38912
	ds_read_b128 v[210:213], v157 offset:39936
	global_load_lds_dwordx4 v134, s[38:39]
	s_mov_b32 m0, s35
	s_nop 0
	global_load_lds_dwordx4 v130, s[38:39]
	s_waitcnt vmcnt(8)
	s_waitcnt lgkmcnt(0)
	s_setprio 1
	s_barrier
	v_mfma_i32_16x16x64_i8 v[124:127], v[144:147], v[182:185], v[124:127]
	v_mfma_i32_16x16x64_i8 v[116:119], v[158:161], v[182:185], v[116:119]
	v_mfma_i32_16x16x64_i8 v[108:111], v[144:147], v[190:193], v[108:111]
	v_mfma_i32_16x16x64_i8 v[100:103], v[158:161], v[190:193], v[100:103]
	v_mfma_i32_16x16x64_i8 v[92:95], v[144:147], v[198:201], v[92:95]
	v_mfma_i32_16x16x64_i8 v[84:87], v[158:161], v[198:201], v[84:87]
	v_mfma_i32_16x16x64_i8 v[76:79], v[144:147], v[206:209], v[76:79]
	v_mfma_i32_16x16x64_i8 v[68:71], v[158:161], v[206:209], v[68:71]
	v_mfma_i32_16x16x64_i8 v[124:127], v[148:151], v[186:189], v[124:127]
	v_mfma_i32_16x16x64_i8 v[116:119], v[162:165], v[186:189], v[116:119]
	v_mfma_i32_16x16x64_i8 v[108:111], v[148:151], v[194:197], v[108:111]
	v_mfma_i32_16x16x64_i8 v[100:103], v[162:165], v[194:197], v[100:103]
	v_mfma_i32_16x16x64_i8 v[92:95], v[148:151], v[202:205], v[92:95]
	v_mfma_i32_16x16x64_i8 v[84:87], v[162:165], v[202:205], v[84:87]
	v_mfma_i32_16x16x64_i8 v[76:79], v[148:151], v[210:213], v[76:79]
	v_mfma_i32_16x16x64_i8 v[68:71], v[162:165], v[210:213], v[68:71]
	v_mfma_i32_16x16x64_i8 v[120:123], v[166:169], v[182:185], v[120:123]
	v_mfma_i32_16x16x64_i8 v[112:115], v[174:177], v[182:185], v[112:115]
	v_mfma_i32_16x16x64_i8 v[104:107], v[166:169], v[190:193], v[104:107]
	v_mfma_i32_16x16x64_i8 v[96:99], v[174:177], v[190:193], v[96:99]
	v_mfma_i32_16x16x64_i8 v[88:91], v[166:169], v[198:201], v[88:91]
	v_mfma_i32_16x16x64_i8 v[80:83], v[174:177], v[198:201], v[80:83]
	v_mfma_i32_16x16x64_i8 v[72:75], v[166:169], v[206:209], v[72:75]
	v_mfma_i32_16x16x64_i8 v[64:67], v[174:177], v[206:209], v[64:67]
	v_mfma_i32_16x16x64_i8 v[120:123], v[170:173], v[186:189], v[120:123]
	v_mfma_i32_16x16x64_i8 v[112:115], v[178:181], v[186:189], v[112:115]
	v_mfma_i32_16x16x64_i8 v[104:107], v[170:173], v[194:197], v[104:107]
	v_mfma_i32_16x16x64_i8 v[96:99], v[178:181], v[194:197], v[96:99]
	v_mfma_i32_16x16x64_i8 v[88:91], v[170:173], v[202:205], v[88:91]
	v_mfma_i32_16x16x64_i8 v[80:83], v[178:181], v[202:205], v[80:83]
	v_mfma_i32_16x16x64_i8 v[72:75], v[170:173], v[210:213], v[72:75]
	v_mfma_i32_16x16x64_i8 v[64:67], v[178:181], v[210:213], v[64:67]
	s_barrier
	s_setprio 0
	s_add_i32 s38, s53, s2
	s_add_i32 m0, s38, -128
	ds_read_b128 v[182:185], v157 offset:49152
	ds_read_b128 v[186:189], v157 offset:50176
	ds_read_b128 v[190:193], v157 offset:51200
	ds_read_b128 v[194:197], v157 offset:52224
	ds_read_b128 v[198:201], v157 offset:53248
	ds_read_b128 v[202:205], v157 offset:54272
	ds_read_b128 v[206:209], v157 offset:55296
	ds_read_b128 v[210:213], v157 offset:56320
	global_load_lds_dwordx4 v132, s[36:37] offset:128
	s_add_i32 m0, s38, 8064
	s_add_u32 s36, s36, 0x80080
	s_addc_u32 s37, s37, 0
	s_add_i32 s38, s54, s2
	global_load_lds_dwordx4 v128, s[98:99] offset:128
	s_mov_b32 m0, s38
	s_nop 0
	global_load_lds_dwordx4 v132, s[36:37]
	s_add_i32 m0, s38, 0x2000
	s_nop 0
	global_load_lds_dwordx4 v128, s[36:37]
	s_add_i32 m0, s42, -128
	s_nop 0
	global_load_lds_dwordx4 v134, s[100:101] offset:128
	s_add_i32 m0, s43, -128
	s_nop 0
	global_load_lds_dwordx4 v130, s[100:101] offset:128
	s_waitcnt vmcnt(8)
	s_waitcnt lgkmcnt(0)
	s_setprio 1
	s_barrier
	v_mfma_i32_16x16x64_i8 v[60:63], v[144:147], v[182:185], v[60:63]
	v_mfma_i32_16x16x64_i8 v[52:55], v[158:161], v[182:185], v[52:55]
	v_mfma_i32_16x16x64_i8 v[44:47], v[144:147], v[190:193], v[44:47]
	v_mfma_i32_16x16x64_i8 v[36:39], v[158:161], v[190:193], v[36:39]
	v_mfma_i32_16x16x64_i8 v[28:31], v[144:147], v[198:201], v[28:31]
	v_mfma_i32_16x16x64_i8 v[20:23], v[158:161], v[198:201], v[20:23]
	v_mfma_i32_16x16x64_i8 v[12:15], v[144:147], v[206:209], v[12:15]
	v_mfma_i32_16x16x64_i8 v[4:7], v[158:161], v[206:209], v[4:7]
	v_mfma_i32_16x16x64_i8 v[60:63], v[148:151], v[186:189], v[60:63]
	v_mfma_i32_16x16x64_i8 v[52:55], v[162:165], v[186:189], v[52:55]
	v_mfma_i32_16x16x64_i8 v[44:47], v[148:151], v[194:197], v[44:47]
	v_mfma_i32_16x16x64_i8 v[36:39], v[162:165], v[194:197], v[36:39]
	v_mfma_i32_16x16x64_i8 v[28:31], v[148:151], v[202:205], v[28:31]
	v_mfma_i32_16x16x64_i8 v[20:23], v[162:165], v[202:205], v[20:23]
	v_mfma_i32_16x16x64_i8 v[12:15], v[148:151], v[210:213], v[12:15]
	v_mfma_i32_16x16x64_i8 v[4:7], v[162:165], v[210:213], v[4:7]
	v_mfma_i32_16x16x64_i8 v[56:59], v[166:169], v[182:185], v[56:59]
	v_mfma_i32_16x16x64_i8 v[48:51], v[174:177], v[182:185], v[48:51]
	v_mfma_i32_16x16x64_i8 v[40:43], v[166:169], v[190:193], v[40:43]
	v_mfma_i32_16x16x64_i8 v[32:35], v[174:177], v[190:193], v[32:35]
	v_mfma_i32_16x16x64_i8 v[24:27], v[166:169], v[198:201], v[24:27]
	v_mfma_i32_16x16x64_i8 v[16:19], v[174:177], v[198:201], v[16:19]
	v_mfma_i32_16x16x64_i8 v[8:11], v[166:169], v[206:209], v[8:11]
	v_mfma_i32_16x16x64_i8 v[0:3], v[174:177], v[206:209], v[0:3]
	v_mfma_i32_16x16x64_i8 v[56:59], v[170:173], v[186:189], v[56:59]
	v_mfma_i32_16x16x64_i8 v[48:51], v[178:181], v[186:189], v[48:51]
	v_mfma_i32_16x16x64_i8 v[40:43], v[170:173], v[194:197], v[40:43]
	v_mfma_i32_16x16x64_i8 v[32:35], v[178:181], v[194:197], v[32:35]
	v_mfma_i32_16x16x64_i8 v[24:27], v[170:173], v[202:205], v[24:27]
	v_mfma_i32_16x16x64_i8 v[16:19], v[178:181], v[202:205], v[16:19]
	v_mfma_i32_16x16x64_i8 v[8:11], v[170:173], v[210:213], v[8:11]
	v_mfma_i32_16x16x64_i8 v[0:3], v[178:181], v[210:213], v[0:3]
	s_barrier
	s_setprio 0
	s_add_i32 s52, s52, 2
	s_add_u32 s30, s30, 0x100
	s_addc_u32 s31, s31, 0
	s_add_u32 s50, s50, 0x100
	s_addc_u32 s51, s51, 0
	s_cmp_gt_u32 s52, 29
	s_cbranch_scc0 .LBB0_773
	s_and_b64 vcc, exec, s[14:15]
	s_cbranch_vccz .LBB0_776
	s_barrier

.LBB0_858:
	ds_read_b128 v[152:155], v149
	ds_read_b128 v[156:159], v149 offset:1024
	ds_read_b128 v[160:163], v149 offset:2048
	ds_read_b128 v[164:167], v149 offset:3072
	ds_read_b128 v[168:171], v150
	ds_read_b128 v[172:175], v150 offset:1024
	ds_read_b128 v[176:179], v150 offset:2048
	ds_read_b128 v[180:183], v150 offset:3072
	s_add_u32 s26, s24, 0x100
	s_addc_u32 s27, s25, 0
	s_cmpk_eq_i32 s54, 0xa8
	s_cselect_b32 s31, s5, s27
	s_cselect_b32 s30, s4, s26
	s_cselect_b32 s29, s23, s53
	s_cselect_b32 s28, s22, s52
	s_add_i32 m0, s33, 0xc000
	ds_read_b128 v[184:187], v151
	ds_read_b128 v[188:191], v151 offset:1024
	ds_read_b128 v[192:195], v151 offset:2048
	ds_read_b128 v[196:199], v151 offset:3072
	ds_read_b128 v[200:203], v151 offset:4096
	ds_read_b128 v[204:207], v151 offset:5120
	ds_read_b128 v[208:211], v151 offset:6144
	ds_read_b128 v[212:215], v151 offset:7168
	global_load_lds_dwordx4 v136, s[24:25]
	s_add_i32 m0, s33, 0xe000
	s_nop 0
	global_load_lds_dwordx4 v138, s[24:25]
	s_waitcnt vmcnt(8)
	s_waitcnt lgkmcnt(0)
	s_setprio 1
	s_barrier
	v_mfma_f32_16x16x32_bf16 v[124:127], v[152:155], v[184:187], v[124:127]
	v_mfma_f32_16x16x32_bf16 v[120:123], v[160:163], v[184:187], v[120:123]
	v_mfma_f32_16x16x32_bf16 v[116:119], v[152:155], v[192:195], v[116:119]
	v_mfma_f32_16x16x32_bf16 v[108:111], v[160:163], v[192:195], v[108:111]
	v_mfma_f32_16x16x32_bf16 v[100:103], v[152:155], v[200:203], v[100:103]
	v_mfma_f32_16x16x32_bf16 v[92:95], v[160:163], v[200:203], v[92:95]
	v_mfma_f32_16x16x32_bf16 v[84:87], v[152:155], v[208:211], v[84:87]
	v_mfma_f32_16x16x32_bf16 v[76:79], v[160:163], v[208:211], v[76:79]
	v_mfma_f32_16x16x32_bf16 v[124:127], v[156:159], v[188:191], v[124:127]
	v_mfma_f32_16x16x32_bf16 v[120:123], v[164:167], v[188:191], v[120:123]
	v_mfma_f32_16x16x32_bf16 v[116:119], v[156:159], v[196:199], v[116:119]
	v_mfma_f32_16x16x32_bf16 v[108:111], v[164:167], v[196:199], v[108:111]
	v_mfma_f32_16x16x32_bf16 v[100:103], v[156:159], v[204:207], v[100:103]
	v_mfma_f32_16x16x32_bf16 v[92:95], v[164:167], v[204:207], v[92:95]
	v_mfma_f32_16x16x32_bf16 v[84:87], v[156:159], v[212:215], v[84:87]
	v_mfma_f32_16x16x32_bf16 v[76:79], v[164:167], v[212:215], v[76:79]
	v_mfma_f32_16x16x32_bf16 v[112:115], v[168:171], v[184:187], v[112:115]
	v_mfma_f32_16x16x32_bf16 v[104:107], v[176:179], v[184:187], v[104:107]
	v_mfma_f32_16x16x32_bf16 v[96:99], v[168:171], v[192:195], v[96:99]
	v_mfma_f32_16x16x32_bf16 v[88:91], v[176:179], v[192:195], v[88:91]
	v_mfma_f32_16x16x32_bf16 v[80:83], v[168:171], v[200:203], v[80:83]
	v_mfma_f32_16x16x32_bf16 v[72:75], v[176:179], v[200:203], v[72:75]
	v_mfma_f32_16x16x32_bf16 v[68:71], v[168:171], v[208:211], v[68:71]
	v_mfma_f32_16x16x32_bf16 v[64:67], v[176:179], v[208:211], v[64:67]
	v_mfma_f32_16x16x32_bf16 v[112:115], v[172:175], v[188:191], v[112:115]
	v_mfma_f32_16x16x32_bf16 v[104:107], v[180:183], v[188:191], v[104:107]
	v_mfma_f32_16x16x32_bf16 v[96:99], v[172:175], v[196:199], v[96:99]
	v_mfma_f32_16x16x32_bf16 v[88:91], v[180:183], v[196:199], v[88:91]
	v_mfma_f32_16x16x32_bf16 v[80:83], v[172:175], v[204:207], v[80:83]
	v_mfma_f32_16x16x32_bf16 v[72:75], v[180:183], v[204:207], v[72:75]
	v_mfma_f32_16x16x32_bf16 v[68:71], v[172:175], v[212:215], v[68:71]
	v_mfma_f32_16x16x32_bf16 v[64:67], v[180:183], v[212:215], v[64:67]
	s_barrier
	s_setprio 0
	s_add_i32 s24, s42, s2
	s_mov_b32 m0, s24
	ds_read_b128 v[184:187], v151 offset:16384
	ds_read_b128 v[188:191], v151 offset:17408
	ds_read_b128 v[192:195], v151 offset:18432
	ds_read_b128 v[196:199], v151 offset:19456
	ds_read_b128 v[200:203], v151 offset:20480
	ds_read_b128 v[204:207], v151 offset:21504
	ds_read_b128 v[208:211], v151 offset:22528
	ds_read_b128 v[212:215], v151 offset:23552
	global_load_lds_dwordx4 v132, s[28:29]
	s_add_i32 m0, s24, 0x2000
	s_add_u32 s24, s28, 0x2b0000
	s_mov_b64 s[98:99], s[28:29]
	s_addc_u32 s25, s29, 0
	s_add_i32 s55, s43, s2
	global_load_lds_dwordx4 v128, s[98:99]
	s_mov_b32 m0, s55
	s_nop 0
	global_load_lds_dwordx4 v132, s[24:25]
	s_add_i32 m0, s55, 0x2000
	s_nop 0
	global_load_lds_dwordx4 v128, s[24:25]
	s_mov_b32 m0, s33
	s_nop 0
	global_load_lds_dwordx4 v134, s[30:31]
	s_mov_b32 m0, s35
	s_nop 0
	global_load_lds_dwordx4 v130, s[30:31]
	s_waitcnt vmcnt(8)
	s_waitcnt lgkmcnt(0)
	s_setprio 1
	s_barrier
	v_mfma_f32_16x16x32_bf16 v[60:63], v[152:155], v[184:187], v[60:63]
	v_mfma_f32_16x16x32_bf16 v[56:59], v[160:163], v[184:187], v[56:59]
	v_mfma_f32_16x16x32_bf16 v[52:55], v[152:155], v[192:195], v[52:55]
	v_mfma_f32_16x16x32_bf16 v[44:47], v[160:163], v[192:195], v[44:47]
	v_mfma_f32_16x16x32_bf16 v[36:39], v[152:155], v[200:203], v[36:39]
	v_mfma_f32_16x16x32_bf16 v[28:31], v[160:163], v[200:203], v[28:31]
	v_mfma_f32_16x16x32_bf16 v[20:23], v[152:155], v[208:211], v[20:23]
	v_mfma_f32_16x16x32_bf16 v[12:15], v[160:163], v[208:211], v[12:15]
	v_mfma_f32_16x16x32_bf16 v[60:63], v[156:159], v[188:191], v[60:63]
	v_mfma_f32_16x16x32_bf16 v[56:59], v[164:167], v[188:191], v[56:59]
	v_mfma_f32_16x16x32_bf16 v[52:55], v[156:159], v[196:199], v[52:55]
	v_mfma_f32_16x16x32_bf16 v[44:47], v[164:167], v[196:199], v[44:47]
	v_mfma_f32_16x16x32_bf16 v[36:39], v[156:159], v[204:207], v[36:39]
	v_mfma_f32_16x16x32_bf16 v[28:31], v[164:167], v[204:207], v[28:31]
	v_mfma_f32_16x16x32_bf16 v[20:23], v[156:159], v[212:215], v[20:23]
	v_mfma_f32_16x16x32_bf16 v[12:15], v[164:167], v[212:215], v[12:15]
	v_mfma_f32_16x16x32_bf16 v[48:51], v[168:171], v[184:187], v[48:51]
	v_mfma_f32_16x16x32_bf16 v[40:43], v[176:179], v[184:187], v[40:43]
	v_mfma_f32_16x16x32_bf16 v[32:35], v[168:171], v[192:195], v[32:35]
	v_mfma_f32_16x16x32_bf16 v[24:27], v[176:179], v[192:195], v[24:27]
	v_mfma_f32_16x16x32_bf16 v[16:19], v[168:171], v[200:203], v[16:19]
	v_mfma_f32_16x16x32_bf16 v[8:11], v[176:179], v[200:203], v[8:11]
	v_mfma_f32_16x16x32_bf16 v[4:7], v[168:171], v[208:211], v[4:7]
	v_mfma_f32_16x16x32_bf16 v[0:3], v[176:179], v[208:211], v[0:3]
	v_mfma_f32_16x16x32_bf16 v[48:51], v[172:175], v[188:191], v[48:51]
	v_mfma_f32_16x16x32_bf16 v[40:43], v[180:183], v[188:191], v[40:43]
	v_mfma_f32_16x16x32_bf16 v[32:35], v[172:175], v[196:199], v[32:35]
	v_mfma_f32_16x16x32_bf16 v[24:27], v[180:183], v[196:199], v[24:27]
	v_mfma_f32_16x16x32_bf16 v[16:19], v[172:175], v[204:207], v[16:19]
	v_mfma_f32_16x16x32_bf16 v[8:11], v[180:183], v[204:207], v[8:11]
	v_mfma_f32_16x16x32_bf16 v[4:7], v[172:175], v[212:215], v[4:7]
	v_mfma_f32_16x16x32_bf16 v[0:3], v[180:183], v[212:215], v[0:3]
	s_barrier
	s_setprio 0
	s_add_i32 s55, 0, 0x18000
	s_add_i32 s58, 0, 0x1c000
	ds_read_b128 v[152:155], v149 offset:32768
	ds_read_b128 v[156:159], v149 offset:33792
	ds_read_b128 v[160:163], v149 offset:34816
	ds_read_b128 v[164:167], v149 offset:35840
	ds_read_b128 v[168:171], v150 offset:32768
	ds_read_b128 v[172:175], v150 offset:33792
	ds_read_b128 v[176:179], v150 offset:34816
	ds_read_b128 v[180:183], v150 offset:35840
	s_add_u32 s24, s30, 0x2b0000
	s_addc_u32 s25, s31, 0
	s_mov_b32 m0, s36
	ds_read_b128 v[184:187], v151 offset:32768
	ds_read_b128 v[188:191], v151 offset:33792
	ds_read_b128 v[192:195], v151 offset:34816
	ds_read_b128 v[196:199], v151 offset:35840
	ds_read_b128 v[200:203], v151 offset:36864
	ds_read_b128 v[204:207], v151 offset:37888
	ds_read_b128 v[208:211], v151 offset:38912
	ds_read_b128 v[212:215], v151 offset:39936
	global_load_lds_dwordx4 v134, s[24:25]
	s_mov_b32 m0, s37
	s_nop 0
	global_load_lds_dwordx4 v130, s[24:25]
	s_waitcnt vmcnt(8)
	s_waitcnt lgkmcnt(0)
	s_setprio 1
	s_barrier
	v_mfma_f32_16x16x32_bf16 v[124:127], v[152:155], v[184:187], v[124:127]
	v_mfma_f32_16x16x32_bf16 v[120:123], v[160:163], v[184:187], v[120:123]
	v_mfma_f32_16x16x32_bf16 v[116:119], v[152:155], v[192:195], v[116:119]
	v_mfma_f32_16x16x32_bf16 v[108:111], v[160:163], v[192:195], v[108:111]
	v_mfma_f32_16x16x32_bf16 v[100:103], v[152:155], v[200:203], v[100:103]
	v_mfma_f32_16x16x32_bf16 v[92:95], v[160:163], v[200:203], v[92:95]
	v_mfma_f32_16x16x32_bf16 v[84:87], v[152:155], v[208:211], v[84:87]
	v_mfma_f32_16x16x32_bf16 v[76:79], v[160:163], v[208:211], v[76:79]
	v_mfma_f32_16x16x32_bf16 v[124:127], v[156:159], v[188:191], v[124:127]
	v_mfma_f32_16x16x32_bf16 v[120:123], v[164:167], v[188:191], v[120:123]
	v_mfma_f32_16x16x32_bf16 v[116:119], v[156:159], v[196:199], v[116:119]
	v_mfma_f32_16x16x32_bf16 v[108:111], v[164:167], v[196:199], v[108:111]
	v_mfma_f32_16x16x32_bf16 v[100:103], v[156:159], v[204:207], v[100:103]
	v_mfma_f32_16x16x32_bf16 v[92:95], v[164:167], v[204:207], v[92:95]
	v_mfma_f32_16x16x32_bf16 v[84:87], v[156:159], v[212:215], v[84:87]
	v_mfma_f32_16x16x32_bf16 v[76:79], v[164:167], v[212:215], v[76:79]
	v_mfma_f32_16x16x32_bf16 v[112:115], v[168:171], v[184:187], v[112:115]
	v_mfma_f32_16x16x32_bf16 v[104:107], v[176:179], v[184:187], v[104:107]
	v_mfma_f32_16x16x32_bf16 v[96:99], v[168:171], v[192:195], v[96:99]
	v_mfma_f32_16x16x32_bf16 v[88:91], v[176:179], v[192:195], v[88:91]
	v_mfma_f32_16x16x32_bf16 v[80:83], v[168:171], v[200:203], v[80:83]
	v_mfma_f32_16x16x32_bf16 v[72:75], v[176:179], v[200:203], v[72:75]
	v_mfma_f32_16x16x32_bf16 v[68:71], v[168:171], v[208:211], v[68:71]
	v_mfma_f32_16x16x32_bf16 v[64:67], v[176:179], v[208:211], v[64:67]
	v_mfma_f32_16x16x32_bf16 v[112:115], v[172:175], v[188:191], v[112:115]
	v_mfma_f32_16x16x32_bf16 v[104:107], v[180:183], v[188:191], v[104:107]
	v_mfma_f32_16x16x32_bf16 v[96:99], v[172:175], v[196:199], v[96:99]
	v_mfma_f32_16x16x32_bf16 v[88:91], v[180:183], v[196:199], v[88:91]
	v_mfma_f32_16x16x32_bf16 v[80:83], v[172:175], v[204:207], v[80:83]
	v_mfma_f32_16x16x32_bf16 v[72:75], v[180:183], v[204:207], v[72:75]
	v_mfma_f32_16x16x32_bf16 v[68:71], v[172:175], v[212:215], v[68:71]
	v_mfma_f32_16x16x32_bf16 v[64:67], v[180:183], v[212:215], v[64:67]
	s_barrier
	s_setprio 0
	s_add_i32 s24, s55, s2
	s_add_i32 m0, s24, -128
	ds_read_b128 v[184:187], v151 offset:49152
	ds_read_b128 v[188:191], v151 offset:50176
	ds_read_b128 v[192:195], v151 offset:51200
	ds_read_b128 v[196:199], v151 offset:52224
	ds_read_b128 v[200:203], v151 offset:53248
	ds_read_b128 v[204:207], v151 offset:54272
	ds_read_b128 v[208:211], v151 offset:55296
	ds_read_b128 v[212:215], v151 offset:56320
	global_load_lds_dwordx4 v132, s[28:29] offset:128
	s_add_i32 m0, s24, 8064
	s_add_u32 s24, s28, 0x2b0080
	s_addc_u32 s25, s29, 0
	s_add_i32 s28, s58, s2
	global_load_lds_dwordx4 v128, s[98:99] offset:128
	s_mov_b32 m0, s28
	s_nop 0
	global_load_lds_dwordx4 v132, s[24:25]
	s_add_i32 m0, s28, 0x2000
	s_nop 0
	global_load_lds_dwordx4 v128, s[24:25]
	s_add_i32 m0, s40, -128
	s_nop 0
	global_load_lds_dwordx4 v134, s[30:31] offset:128
	s_add_i32 m0, s41, -128
	s_nop 0
	global_load_lds_dwordx4 v130, s[30:31] offset:128
	s_waitcnt vmcnt(8)
	s_waitcnt lgkmcnt(0)
	s_setprio 1
	s_barrier
	v_mfma_f32_16x16x32_bf16 v[60:63], v[152:155], v[184:187], v[60:63]
	v_mfma_f32_16x16x32_bf16 v[56:59], v[160:163], v[184:187], v[56:59]
	v_mfma_f32_16x16x32_bf16 v[52:55], v[152:155], v[192:195], v[52:55]
	v_mfma_f32_16x16x32_bf16 v[44:47], v[160:163], v[192:195], v[44:47]
	v_mfma_f32_16x16x32_bf16 v[36:39], v[152:155], v[200:203], v[36:39]
	v_mfma_f32_16x16x32_bf16 v[28:31], v[160:163], v[200:203], v[28:31]
	v_mfma_f32_16x16x32_bf16 v[20:23], v[152:155], v[208:211], v[20:23]
	v_mfma_f32_16x16x32_bf16 v[12:15], v[160:163], v[208:211], v[12:15]
	v_mfma_f32_16x16x32_bf16 v[60:63], v[156:159], v[188:191], v[60:63]
	v_mfma_f32_16x16x32_bf16 v[56:59], v[164:167], v[188:191], v[56:59]
	v_mfma_f32_16x16x32_bf16 v[52:55], v[156:159], v[196:199], v[52:55]
	v_mfma_f32_16x16x32_bf16 v[44:47], v[164:167], v[196:199], v[44:47]
	v_mfma_f32_16x16x32_bf16 v[36:39], v[156:159], v[204:207], v[36:39]
	v_mfma_f32_16x16x32_bf16 v[28:31], v[164:167], v[204:207], v[28:31]
	v_mfma_f32_16x16x32_bf16 v[20:23], v[156:159], v[212:215], v[20:23]
	v_mfma_f32_16x16x32_bf16 v[12:15], v[164:167], v[212:215], v[12:15]
	v_mfma_f32_16x16x32_bf16 v[48:51], v[168:171], v[184:187], v[48:51]
	v_mfma_f32_16x16x32_bf16 v[40:43], v[176:179], v[184:187], v[40:43]
	v_mfma_f32_16x16x32_bf16 v[32:35], v[168:171], v[192:195], v[32:35]
	v_mfma_f32_16x16x32_bf16 v[24:27], v[176:179], v[192:195], v[24:27]
	v_mfma_f32_16x16x32_bf16 v[16:19], v[168:171], v[200:203], v[16:19]
	v_mfma_f32_16x16x32_bf16 v[8:11], v[176:179], v[200:203], v[8:11]
	v_mfma_f32_16x16x32_bf16 v[4:7], v[168:171], v[208:211], v[4:7]
	v_mfma_f32_16x16x32_bf16 v[0:3], v[176:179], v[208:211], v[0:3]
	v_mfma_f32_16x16x32_bf16 v[48:51], v[172:175], v[188:191], v[48:51]
	v_mfma_f32_16x16x32_bf16 v[40:43], v[180:183], v[188:191], v[40:43]
	v_mfma_f32_16x16x32_bf16 v[32:35], v[172:175], v[196:199], v[32:35]
	v_mfma_f32_16x16x32_bf16 v[24:27], v[180:183], v[196:199], v[24:27]
	v_mfma_f32_16x16x32_bf16 v[16:19], v[172:175], v[204:207], v[16:19]
	v_mfma_f32_16x16x32_bf16 v[8:11], v[180:183], v[204:207], v[8:11]
	v_mfma_f32_16x16x32_bf16 v[4:7], v[172:175], v[212:215], v[4:7]
	v_mfma_f32_16x16x32_bf16 v[0:3], v[180:183], v[212:215], v[0:3]
	s_barrier
	s_setprio 0
	s_add_i32 s54, s54, 2
	s_add_u32 s52, s52, 0x100
	s_addc_u32 s53, s53, 0
	s_cmpk_gt_u32 s54, 0xa9
	s_mov_b64 s[24:25], s[26:27]
	s_cbranch_scc0 .LBB0_858
	s_and_b64 vcc, exec, s[10:11]
	s_cbranch_vccz .LBB0_861
	s_barrier
